# v14 + LayerNorm-epilogue row statistics: 64 ds_bpermute round trips (lane^16 / lane^32) replaced by v_permlane16/32_swap
# speedup vs baseline: 1.0298x; 1.0032x over previous
.LBB0_46:
	s_lshl_b32 s4, s28, 5
	s_lshl_b32 s5, s6, 8
	s_or_b32 s4, s5, s4
	v_lshrrev_b32_e32 v128, 2, v145
	s_lshl_b32 s14, s27, 8
	v_and_or_b32 v138, v128, 12, s4
	s_add_i32 s4, s14, s24
	v_or_b32_e32 v146, s4, v144
	s_barrier
	s_mov_b32 s4, 0x3fb504f3
	v_lshl_add_u32 v128, v146, 11, v138
	v_lshl_add_u64 v[130:131], v[128:129], 2, s[0:1]
	global_load_dwordx4 v[134:137], v[130:131], off nt
	global_load_dwordx4 v[140:143], v[130:131], off offset:64 nt
	global_load_dwordx4 v[148:151], v[130:131], off offset:512 nt
	global_load_dwordx4 v[152:155], v[130:131], off offset:576 nt
	v_add_u32_e32 v130, 0x8000, v128
	v_mov_b32_e32 v131, v129
	v_lshl_add_u64 v[130:131], v[130:131], 2, s[0:1]
	global_load_dwordx4 v[156:159], v[130:131], off nt
	global_load_dwordx4 v[160:163], v[130:131], off offset:64 nt
	global_load_dwordx4 v[164:167], v[130:131], off offset:512 nt
	global_load_dwordx4 v[168:171], v[130:131], off offset:576 nt
	v_add_u32_e32 v130, 0x10000, v128
	v_mov_b32_e32 v131, v129
	v_lshl_add_u64 v[130:131], v[130:131], 2, s[0:1]
	global_load_dwordx4 v[172:175], v[130:131], off nt
	global_load_dwordx4 v[176:179], v[130:131], off offset:64 nt
	global_load_dwordx4 v[180:183], v[130:131], off offset:512 nt
	global_load_dwordx4 v[184:187], v[130:131], off offset:576 nt
	v_add_u32_e32 v130, 0x18000, v128
	v_mov_b32_e32 v131, v129
	v_lshl_add_u64 v[130:131], v[130:131], 2, s[0:1]
	global_load_dwordx4 v[188:191], v[130:131], off nt
	global_load_dwordx4 v[192:195], v[130:131], off offset:64 nt
	global_load_dwordx4 v[196:199], v[130:131], off offset:512 nt
	global_load_dwordx4 v[200:203], v[130:131], off offset:576 nt
	v_add_u32_e32 v130, 0x40000, v128
	v_mov_b32_e32 v131, v129
	v_lshl_add_u64 v[130:131], v[130:131], 2, s[0:1]
	v_and_b32_e32 v132, 63, v145
	v_cmp_gt_u32_e32 vcc, 16, v132
	s_waitcnt vmcnt(0)
	v_pk_fma_f32 v[94:95], v[136:137], s[4:5], v[94:95] op_sel_hi:[1,0,1]
	v_pk_fma_f32 v[92:93], v[134:135], s[4:5], v[92:93] op_sel_hi:[1,0,1]
	v_pk_fma_f32 v[62:63], v[142:143], s[4:5], v[62:63] op_sel_hi:[1,0,1]
	v_pk_fma_f32 v[60:61], v[140:141], s[4:5], v[60:61] op_sel_hi:[1,0,1]
	v_pk_fma_f32 v[30:31], v[150:151], s[4:5], v[30:31] op_sel_hi:[1,0,1]
	v_pk_fma_f32 v[28:29], v[148:149], s[4:5], v[28:29] op_sel_hi:[1,0,1]
	v_pk_fma_f32 v[14:15], v[154:155], s[4:5], v[14:15] op_sel_hi:[1,0,1]
	v_pk_fma_f32 v[12:13], v[152:153], s[4:5], v[12:13] op_sel_hi:[1,0,1]
	v_pk_fma_f32 v[90:91], v[158:159], s[4:5], v[90:91] op_sel_hi:[1,0,1]
	v_pk_fma_f32 v[88:89], v[156:157], s[4:5], v[88:89] op_sel_hi:[1,0,1]
	v_pk_fma_f32 v[58:59], v[162:163], s[4:5], v[58:59] op_sel_hi:[1,0,1]
	v_pk_fma_f32 v[56:57], v[160:161], s[4:5], v[56:57] op_sel_hi:[1,0,1]
	v_pk_fma_f32 v[26:27], v[166:167], s[4:5], v[26:27] op_sel_hi:[1,0,1]
	v_pk_fma_f32 v[24:25], v[164:165], s[4:5], v[24:25] op_sel_hi:[1,0,1]
	v_pk_fma_f32 v[10:11], v[170:171], s[4:5], v[10:11] op_sel_hi:[1,0,1]
	v_pk_fma_f32 v[8:9], v[168:169], s[4:5], v[8:9] op_sel_hi:[1,0,1]
	v_pk_fma_f32 v[86:87], v[174:175], s[4:5], v[86:87] op_sel_hi:[1,0,1]
	v_pk_fma_f32 v[84:85], v[172:173], s[4:5], v[84:85] op_sel_hi:[1,0,1]
	v_pk_fma_f32 v[54:55], v[178:179], s[4:5], v[54:55] op_sel_hi:[1,0,1]
	v_pk_fma_f32 v[52:53], v[176:177], s[4:5], v[52:53] op_sel_hi:[1,0,1]
	v_pk_fma_f32 v[22:23], v[182:183], s[4:5], v[22:23] op_sel_hi:[1,0,1]
	v_pk_fma_f32 v[20:21], v[180:181], s[4:5], v[20:21] op_sel_hi:[1,0,1]
	v_pk_fma_f32 v[6:7], v[186:187], s[4:5], v[6:7] op_sel_hi:[1,0,1]
	v_pk_fma_f32 v[4:5], v[184:185], s[4:5], v[4:5] op_sel_hi:[1,0,1]
	v_pk_fma_f32 v[82:83], v[190:191], s[4:5], v[82:83] op_sel_hi:[1,0,1]
	v_pk_fma_f32 v[80:81], v[188:189], s[4:5], v[80:81] op_sel_hi:[1,0,1]
	v_pk_fma_f32 v[50:51], v[194:195], s[4:5], v[50:51] op_sel_hi:[1,0,1]
	v_pk_fma_f32 v[48:49], v[192:193], s[4:5], v[48:49] op_sel_hi:[1,0,1]
	v_pk_fma_f32 v[18:19], v[198:199], s[4:5], v[18:19] op_sel_hi:[1,0,1]
	v_pk_fma_f32 v[16:17], v[196:197], s[4:5], v[16:17] op_sel_hi:[1,0,1]
	v_pk_fma_f32 v[2:3], v[202:203], s[4:5], v[2:3] op_sel_hi:[1,0,1]
	v_pk_fma_f32 v[0:1], v[200:201], s[4:5], v[0:1] op_sel_hi:[1,0,1]
	s_nop 0
	global_load_dwordx4 v[134:137], v[130:131], off nt
	global_load_dwordx4 v[140:143], v[130:131], off offset:64 nt
	global_load_dwordx4 v[148:151], v[130:131], off offset:512 nt
	global_load_dwordx4 v[152:155], v[130:131], off offset:576 nt
	v_add_u32_e32 v130, 0x48000, v128
	v_mov_b32_e32 v131, v129
	v_lshl_add_u64 v[130:131], v[130:131], 2, s[0:1]
	global_load_dwordx4 v[156:159], v[130:131], off nt
	global_load_dwordx4 v[160:163], v[130:131], off offset:64 nt
	global_load_dwordx4 v[164:167], v[130:131], off offset:512 nt
	global_load_dwordx4 v[168:171], v[130:131], off offset:576 nt
	v_add_u32_e32 v130, 0x50000, v128
	v_mov_b32_e32 v131, v129
	v_lshl_add_u64 v[130:131], v[130:131], 2, s[0:1]
	v_add_u32_e32 v128, 0x58000, v128
	global_load_dwordx4 v[172:175], v[130:131], off nt
	global_load_dwordx4 v[176:179], v[130:131], off offset:64 nt
	global_load_dwordx4 v[180:183], v[130:131], off offset:512 nt
	global_load_dwordx4 v[184:187], v[130:131], off offset:576 nt
	v_lshl_add_u64 v[130:131], v[128:129], 2, s[0:1]
	global_load_dwordx4 v[188:191], v[130:131], off nt
	global_load_dwordx4 v[192:195], v[130:131], off offset:64 nt
	global_load_dwordx4 v[196:199], v[130:131], off offset:512 nt
	global_load_dwordx4 v[200:203], v[130:131], off offset:576 nt
	v_lshlrev_b32_e32 v128, 2, v132
	v_xor_b32_e32 v130, 64, v128
	v_xor_b32_e32 v128, 0x80, v128
	s_waitcnt vmcnt(15)
	v_pk_fma_f32 v[126:127], v[136:137], s[4:5], v[126:127] op_sel_hi:[1,0,1]
	v_pk_fma_f32 v[124:125], v[134:135], s[4:5], v[124:125] op_sel_hi:[1,0,1]
	v_mov_b32_e32 v134, v93
	v_mov_b32_e32 v135, v94
	v_mov_b32_e32 v136, v92
	v_mov_b32_e32 v137, v95
	s_waitcnt vmcnt(14)
	v_pk_fma_f32 v[108:109], v[140:141], s[4:5], v[108:109] op_sel_hi:[1,0,1]
	v_pk_add_f32 v[134:135], v[134:135], v[136:137]
	v_mov_b32_e32 v136, v61
	v_mov_b32_e32 v137, v62
	v_mov_b32_e32 v140, v60
	v_mov_b32_e32 v141, v63
	v_pk_add_f32 v[136:137], v[136:137], v[140:141]
	v_add_f32_e32 v131, v134, v135
	v_pk_add_f32 v[136:137], v[136:137], v[136:137] op_sel_hi:[0,1]
	v_pk_fma_f32 v[110:111], v[142:143], s[4:5], v[110:111] op_sel_hi:[1,0,1]
	v_add_f32_e32 v135, 0, v131
	v_add_f32_e32 v141, v28, v29
	v_add_f32_e32 v143, v30, v31
	v_mov_b32_e32 v140, v12
	v_mov_b32_e32 v142, v13
	v_mov_b32_e32 v136, v14
	v_mov_b32_e32 v134, v15
	v_pk_add_f32 v[140:141], v[140:141], v[142:143]
	v_pk_add_f32 v[134:135], v[136:137], v[134:135]
	s_waitcnt vmcnt(13)
	v_pk_fma_f32 v[78:79], v[150:151], s[4:5], v[78:79] op_sel_hi:[1,0,1]
	v_pk_add_f32 v[134:135], v[140:141], v[134:135]
	v_pk_fma_f32 v[76:77], v[148:149], s[4:5], v[76:77] op_sel_hi:[1,0,1]
	v_add_f32_e32 v131, v134, v135
	v_mov_b32_e32 v218, v131
	v_mov_b32_e32 v133, v131
	s_nop 1
	v_permlane16_swap_b32_e32 v218, v133
	s_waitcnt vmcnt(12)
	v_pk_fma_f32 v[46:47], v[154:155], s[4:5], v[46:47] op_sel_hi:[1,0,1]
	v_pk_fma_f32 v[44:45], v[152:153], s[4:5], v[44:45] op_sel_hi:[1,0,1]
	s_waitcnt vmcnt(11)
	v_pk_fma_f32 v[122:123], v[158:159], s[4:5], v[122:123] op_sel_hi:[1,0,1]
	v_pk_fma_f32 v[120:121], v[156:157], s[4:5], v[120:121] op_sel_hi:[1,0,1]
	s_waitcnt lgkmcnt(0)
	v_add_f32_e32 v131, v218, v133
	v_mov_b32_e32 v218, v131
	v_mov_b32_e32 v133, v131
	s_nop 1
	v_permlane32_swap_b32_e32 v218, v133
	s_waitcnt vmcnt(10)
	v_pk_fma_f32 v[106:107], v[162:163], s[4:5], v[106:107] op_sel_hi:[1,0,1]
	v_pk_fma_f32 v[104:105], v[160:161], s[4:5], v[104:105] op_sel_hi:[1,0,1]
	s_waitcnt vmcnt(9)
	v_pk_fma_f32 v[74:75], v[166:167], s[4:5], v[74:75] op_sel_hi:[1,0,1]
	v_pk_fma_f32 v[72:73], v[164:165], s[4:5], v[72:73] op_sel_hi:[1,0,1]
	s_waitcnt lgkmcnt(0)
	v_add_f32_e32 v131, v218, v133
	v_fmamk_f32 v134, v131, 0xbc800000, v95
	v_fmamk_f32 v136, v131, 0xbc800000, v93
	v_fmamk_f32 v133, v131, 0xbc800000, v94
	v_fmamk_f32 v135, v131, 0xbc800000, v92
	v_mul_f32_e32 v136, v136, v136
	v_mul_f32_e32 v134, v134, v134
	v_fmac_f32_e32 v136, v135, v135
	v_fmac_f32_e32 v134, v133, v133
	v_fmamk_f32 v135, v131, 0xbc800000, v63
	v_fmamk_f32 v137, v131, 0xbc800000, v61
	v_add_f32_e32 v133, v136, v134
	v_fmamk_f32 v134, v131, 0xbc800000, v62
	v_fmamk_f32 v136, v131, 0xbc800000, v60
	v_mul_f32_e32 v137, v137, v137
	v_mul_f32_e32 v135, v135, v135
	v_fmac_f32_e32 v137, v136, v136
	v_fmac_f32_e32 v135, v134, v134
	v_add_f32_e32 v134, v137, v135
	v_fmamk_f32 v135, v131, 0xbc800000, v31
	v_fmamk_f32 v137, v131, 0xbc800000, v29
	v_add_f32_e32 v133, v133, v134
	v_fmamk_f32 v134, v131, 0xbc800000, v30
	v_fmamk_f32 v136, v131, 0xbc800000, v28
	v_mul_f32_e32 v137, v137, v137
	v_mul_f32_e32 v135, v135, v135
	v_fmac_f32_e32 v137, v136, v136
	v_fmac_f32_e32 v135, v134, v134
	v_add_f32_e32 v134, v137, v135
	v_fmamk_f32 v135, v131, 0xbc800000, v15
	v_fmamk_f32 v137, v131, 0xbc800000, v13
	v_add_f32_e32 v133, v134, v133
	v_fmamk_f32 v134, v131, 0xbc800000, v14
	v_fmamk_f32 v136, v131, 0xbc800000, v12
	v_mul_f32_e32 v137, v137, v137
	v_mul_f32_e32 v135, v135, v135
	v_fmac_f32_e32 v137, v136, v136
	v_fmac_f32_e32 v135, v134, v134
	v_add_f32_e32 v134, v137, v135
	v_add_f32_e32 v133, v134, v133
	v_mov_b32_e32 v218, v133
	v_mov_b32_e32 v134, v133
	s_nop 1
	v_permlane16_swap_b32_e32 v218, v134
	s_waitcnt vmcnt(8)
	v_pk_fma_f32 v[42:43], v[170:171], s[4:5], v[42:43] op_sel_hi:[1,0,1]
	v_pk_fma_f32 v[40:41], v[168:169], s[4:5], v[40:41] op_sel_hi:[1,0,1]
	s_waitcnt vmcnt(7)
	v_pk_fma_f32 v[118:119], v[174:175], s[4:5], v[118:119] op_sel_hi:[1,0,1]
	v_pk_fma_f32 v[116:117], v[172:173], s[4:5], v[116:117] op_sel_hi:[1,0,1]
	s_waitcnt lgkmcnt(0)
	v_add_f32_e32 v133, v218, v134
	v_mov_b32_e32 v218, v133
	v_mov_b32_e32 v134, v133
	s_nop 1
	v_permlane32_swap_b32_e32 v218, v134
	s_waitcnt vmcnt(6)
	v_pk_fma_f32 v[102:103], v[178:179], s[4:5], v[102:103] op_sel_hi:[1,0,1]
	v_pk_fma_f32 v[100:101], v[176:177], s[4:5], v[100:101] op_sel_hi:[1,0,1]
	s_waitcnt vmcnt(5)
	v_pk_fma_f32 v[70:71], v[182:183], s[4:5], v[70:71] op_sel_hi:[1,0,1]
	v_pk_fma_f32 v[68:69], v[180:181], s[4:5], v[68:69] op_sel_hi:[1,0,1]
	s_waitcnt vmcnt(4)
	v_pk_fma_f32 v[38:39], v[186:187], s[4:5], v[38:39] op_sel_hi:[1,0,1]
	v_pk_fma_f32 v[36:37], v[184:185], s[4:5], v[36:37] op_sel_hi:[1,0,1]
	s_waitcnt vmcnt(3)
	v_pk_fma_f32 v[114:115], v[190:191], s[4:5], v[114:115] op_sel_hi:[1,0,1]
	v_pk_fma_f32 v[112:113], v[188:189], s[4:5], v[112:113] op_sel_hi:[1,0,1]
	s_waitcnt vmcnt(2)
	v_pk_fma_f32 v[98:99], v[194:195], s[4:5], v[98:99] op_sel_hi:[1,0,1]
	v_pk_fma_f32 v[96:97], v[192:193], s[4:5], v[96:97] op_sel_hi:[1,0,1]
	s_waitcnt vmcnt(1)
	v_pk_fma_f32 v[66:67], v[198:199], s[4:5], v[66:67] op_sel_hi:[1,0,1]
	v_pk_fma_f32 v[64:65], v[196:197], s[4:5], v[64:65] op_sel_hi:[1,0,1]
	s_waitcnt vmcnt(0)
	v_pk_fma_f32 v[34:35], v[202:203], s[4:5], v[34:35] op_sel_hi:[1,0,1]
	v_pk_fma_f32 v[32:33], v[200:201], s[4:5], v[32:33] op_sel_hi:[1,0,1]
	s_lshl_b32 s4, s28, 3
	s_add_i32 s8, s4, 0
	s_and_saveexec_b64 s[4:5], vcc
	v_readlane_b32 s30, v255, 3
	v_readlane_b32 s31, v255, 4
	s_cbranch_execz .LBB0_48
	s_lshl_b32 s9, s26, 11
	s_add_i32 s9, s8, s9
	v_mul_f32_e32 v136, 0x3c800000, v131
	v_lshl_add_u32 v131, v144, 5, s9
	s_waitcnt lgkmcnt(0)
	v_add_f32_e32 v137, v218, v134
	ds_write_b64 v131, v[136:137]
.LBB0_48:
	s_or_b64 exec, exec, s[4:5]
	s_waitcnt lgkmcnt(0)
	v_mov_b32_e32 v134, v89
	v_mov_b32_e32 v135, v90
	v_mov_b32_e32 v136, v88
	v_mov_b32_e32 v137, v91
	v_pk_add_f32 v[134:135], v[134:135], v[136:137]
	v_mov_b32_e32 v136, v57
	v_mov_b32_e32 v137, v58
	v_mov_b32_e32 v140, v56
	v_mov_b32_e32 v141, v59
	v_pk_add_f32 v[136:137], v[136:137], v[140:141]
	v_add_f32_e32 v131, v134, v135
	v_pk_add_f32 v[136:137], v[136:137], v[136:137] op_sel_hi:[0,1]
	v_add_f32_e32 v135, 0, v131
	v_add_f32_e32 v141, v24, v25
	v_add_f32_e32 v143, v26, v27
	v_mov_b32_e32 v140, v8
	v_mov_b32_e32 v142, v9
	v_mov_b32_e32 v136, v10
	v_mov_b32_e32 v134, v11
	v_pk_add_f32 v[140:141], v[140:141], v[142:143]
	v_pk_add_f32 v[134:135], v[136:137], v[134:135]
	s_nop 0
	v_pk_add_f32 v[134:135], v[140:141], v[134:135]
	s_nop 0
	v_add_f32_e32 v131, v134, v135
	v_mov_b32_e32 v218, v131
	v_mov_b32_e32 v133, v131
	s_nop 1
	v_permlane16_swap_b32_e32 v218, v133
	s_waitcnt lgkmcnt(0)
	v_add_f32_e32 v131, v218, v133
	v_mov_b32_e32 v218, v131
	v_mov_b32_e32 v133, v131
	s_nop 1
	v_permlane32_swap_b32_e32 v218, v133
	s_waitcnt lgkmcnt(0)
	v_add_f32_e32 v131, v218, v133
	v_fmamk_f32 v134, v131, 0xbc800000, v91
	v_fmamk_f32 v136, v131, 0xbc800000, v89
	v_fmamk_f32 v133, v131, 0xbc800000, v90
	v_fmamk_f32 v135, v131, 0xbc800000, v88
	v_mul_f32_e32 v136, v136, v136
	v_mul_f32_e32 v134, v134, v134
	v_fmac_f32_e32 v136, v135, v135
	v_fmac_f32_e32 v134, v133, v133
	v_fmamk_f32 v135, v131, 0xbc800000, v59
	v_fmamk_f32 v137, v131, 0xbc800000, v57
	v_add_f32_e32 v133, v136, v134
	v_fmamk_f32 v134, v131, 0xbc800000, v58
	v_fmamk_f32 v136, v131, 0xbc800000, v56
	v_mul_f32_e32 v137, v137, v137
	v_mul_f32_e32 v135, v135, v135
	v_fmac_f32_e32 v137, v136, v136
	v_fmac_f32_e32 v135, v134, v134
	v_add_f32_e32 v134, v137, v135
	v_fmamk_f32 v135, v131, 0xbc800000, v27
	v_fmamk_f32 v137, v131, 0xbc800000, v25
	v_add_f32_e32 v133, v133, v134
	v_fmamk_f32 v134, v131, 0xbc800000, v26
	v_fmamk_f32 v136, v131, 0xbc800000, v24
	v_mul_f32_e32 v137, v137, v137
	v_mul_f32_e32 v135, v135, v135
	v_fmac_f32_e32 v137, v136, v136
	v_fmac_f32_e32 v135, v134, v134
	v_add_f32_e32 v134, v137, v135
	v_fmamk_f32 v135, v131, 0xbc800000, v11
	v_fmamk_f32 v137, v131, 0xbc800000, v9
	v_add_f32_e32 v133, v134, v133
	v_fmamk_f32 v134, v131, 0xbc800000, v10
	v_fmamk_f32 v136, v131, 0xbc800000, v8
	v_mul_f32_e32 v137, v137, v137
	v_mul_f32_e32 v135, v135, v135
	v_fmac_f32_e32 v137, v136, v136
	v_fmac_f32_e32 v135, v134, v134
	v_add_f32_e32 v134, v137, v135
	v_add_f32_e32 v133, v134, v133
	v_mov_b32_e32 v218, v133
	v_mov_b32_e32 v134, v133
	s_nop 1
	v_permlane16_swap_b32_e32 v218, v134
	s_waitcnt lgkmcnt(0)
	v_add_f32_e32 v133, v218, v134
	v_mov_b32_e32 v218, v133
	v_mov_b32_e32 v134, v133
	s_nop 1
	v_permlane32_swap_b32_e32 v218, v134
	s_and_saveexec_b64 s[4:5], vcc
	s_cbranch_execz .LBB0_50
	s_lshl_b32 s9, s26, 11
	s_add_i32 s9, s8, s9
	v_mul_f32_e32 v136, 0x3c800000, v131
	v_lshl_add_u32 v131, v144, 5, s9
	s_waitcnt lgkmcnt(0)
	v_add_f32_e32 v137, v218, v134
	ds_write_b64 v131, v[136:137] offset:512
.LBB0_50:
	s_or_b64 exec, exec, s[4:5]
	s_waitcnt lgkmcnt(0)
	v_mov_b32_e32 v134, v85
	v_mov_b32_e32 v135, v86
	v_mov_b32_e32 v136, v84
	v_mov_b32_e32 v137, v87
	v_pk_add_f32 v[134:135], v[134:135], v[136:137]
	v_mov_b32_e32 v136, v53
	v_mov_b32_e32 v137, v54
	v_mov_b32_e32 v140, v52
	v_mov_b32_e32 v141, v55
	v_pk_add_f32 v[136:137], v[136:137], v[140:141]
	v_add_f32_e32 v131, v134, v135
	v_pk_add_f32 v[136:137], v[136:137], v[136:137] op_sel_hi:[0,1]
	v_add_f32_e32 v135, 0, v131
	v_add_f32_e32 v141, v20, v21
	v_add_f32_e32 v143, v22, v23
	v_mov_b32_e32 v140, v4
	v_mov_b32_e32 v142, v5
	v_mov_b32_e32 v136, v6
	v_mov_b32_e32 v134, v7
	v_pk_add_f32 v[140:141], v[140:141], v[142:143]
	v_pk_add_f32 v[134:135], v[136:137], v[134:135]
	s_nop 0
	v_pk_add_f32 v[134:135], v[140:141], v[134:135]
	s_nop 0
	v_add_f32_e32 v131, v134, v135
	v_mov_b32_e32 v218, v131
	v_mov_b32_e32 v133, v131
	s_nop 1
	v_permlane16_swap_b32_e32 v218, v133
	s_waitcnt lgkmcnt(0)
	v_add_f32_e32 v131, v218, v133
	v_mov_b32_e32 v218, v131
	v_mov_b32_e32 v133, v131
	s_nop 1
	v_permlane32_swap_b32_e32 v218, v133
	s_waitcnt lgkmcnt(0)
	v_add_f32_e32 v131, v218, v133
	v_fmamk_f32 v134, v131, 0xbc800000, v87
	v_fmamk_f32 v136, v131, 0xbc800000, v85
	v_fmamk_f32 v133, v131, 0xbc800000, v86
	v_fmamk_f32 v135, v131, 0xbc800000, v84
	v_mul_f32_e32 v136, v136, v136
	v_mul_f32_e32 v134, v134, v134
	v_fmac_f32_e32 v136, v135, v135
	v_fmac_f32_e32 v134, v133, v133
	v_fmamk_f32 v135, v131, 0xbc800000, v55
	v_fmamk_f32 v137, v131, 0xbc800000, v53
	v_add_f32_e32 v133, v136, v134
	v_fmamk_f32 v134, v131, 0xbc800000, v54
	v_fmamk_f32 v136, v131, 0xbc800000, v52
	v_mul_f32_e32 v137, v137, v137
	v_mul_f32_e32 v135, v135, v135
	v_fmac_f32_e32 v137, v136, v136
	v_fmac_f32_e32 v135, v134, v134
	v_add_f32_e32 v134, v137, v135
	v_fmamk_f32 v135, v131, 0xbc800000, v23
	v_fmamk_f32 v137, v131, 0xbc800000, v21
	v_add_f32_e32 v133, v133, v134
	v_fmamk_f32 v134, v131, 0xbc800000, v22
	v_fmamk_f32 v136, v131, 0xbc800000, v20
	v_mul_f32_e32 v137, v137, v137
	v_mul_f32_e32 v135, v135, v135
	v_fmac_f32_e32 v137, v136, v136
	v_fmac_f32_e32 v135, v134, v134
	v_add_f32_e32 v134, v137, v135
	v_fmamk_f32 v135, v131, 0xbc800000, v7
	v_fmamk_f32 v137, v131, 0xbc800000, v5
	v_add_f32_e32 v133, v134, v133
	v_fmamk_f32 v134, v131, 0xbc800000, v6
	v_fmamk_f32 v136, v131, 0xbc800000, v4
	v_mul_f32_e32 v137, v137, v137
	v_mul_f32_e32 v135, v135, v135
	v_fmac_f32_e32 v137, v136, v136
	v_fmac_f32_e32 v135, v134, v134
	v_add_f32_e32 v134, v137, v135
	v_add_f32_e32 v133, v134, v133
	v_mov_b32_e32 v218, v133
	v_mov_b32_e32 v134, v133
	s_nop 1
	v_permlane16_swap_b32_e32 v218, v134
	s_waitcnt lgkmcnt(0)
	v_add_f32_e32 v133, v218, v134
	v_mov_b32_e32 v218, v133
	v_mov_b32_e32 v134, v133
	s_nop 1
	v_permlane32_swap_b32_e32 v218, v134
	s_and_saveexec_b64 s[4:5], vcc
	s_cbranch_execz .LBB0_52
	s_lshl_b32 s9, s26, 11
	s_add_i32 s9, s8, s9
	v_mul_f32_e32 v136, 0x3c800000, v131
	v_lshl_add_u32 v131, v144, 5, s9
	s_waitcnt lgkmcnt(0)
	v_add_f32_e32 v137, v218, v134
	ds_write_b64 v131, v[136:137] offset:1024
.LBB0_52:
	s_or_b64 exec, exec, s[4:5]
	s_waitcnt lgkmcnt(0)
	v_mov_b32_e32 v134, v81
	v_mov_b32_e32 v135, v82
	v_mov_b32_e32 v136, v80
	v_mov_b32_e32 v137, v83
	v_pk_add_f32 v[134:135], v[134:135], v[136:137]
	v_mov_b32_e32 v136, v49
	v_mov_b32_e32 v137, v50
	v_mov_b32_e32 v140, v48
	v_mov_b32_e32 v141, v51
	v_pk_add_f32 v[136:137], v[136:137], v[140:141]
	v_add_f32_e32 v131, v134, v135
	v_pk_add_f32 v[136:137], v[136:137], v[136:137] op_sel_hi:[0,1]
	v_add_f32_e32 v135, 0, v131
	v_add_f32_e32 v141, v16, v17
	v_add_f32_e32 v143, v18, v19
	v_mov_b32_e32 v140, v0
	v_mov_b32_e32 v142, v1
	v_mov_b32_e32 v136, v2
	v_mov_b32_e32 v134, v3
	v_pk_add_f32 v[140:141], v[140:141], v[142:143]
	v_pk_add_f32 v[134:135], v[136:137], v[134:135]
	s_nop 0
	v_pk_add_f32 v[134:135], v[140:141], v[134:135]
	s_nop 0
	v_add_f32_e32 v131, v134, v135
	v_mov_b32_e32 v218, v131
	v_mov_b32_e32 v133, v131
	s_nop 1
	v_permlane16_swap_b32_e32 v218, v133
	s_waitcnt lgkmcnt(0)
	v_add_f32_e32 v131, v218, v133
	v_mov_b32_e32 v218, v131
	v_mov_b32_e32 v133, v131
	s_nop 1
	v_permlane32_swap_b32_e32 v218, v133
	s_waitcnt lgkmcnt(0)
	v_add_f32_e32 v131, v218, v133
	v_fmamk_f32 v134, v131, 0xbc800000, v83
	v_fmamk_f32 v136, v131, 0xbc800000, v81
	v_fmamk_f32 v133, v131, 0xbc800000, v82
	v_fmamk_f32 v135, v131, 0xbc800000, v80
	v_mul_f32_e32 v136, v136, v136
	v_mul_f32_e32 v134, v134, v134
	v_fmac_f32_e32 v136, v135, v135
	v_fmac_f32_e32 v134, v133, v133
	v_fmamk_f32 v135, v131, 0xbc800000, v51
	v_fmamk_f32 v137, v131, 0xbc800000, v49
	v_add_f32_e32 v133, v136, v134
	v_fmamk_f32 v134, v131, 0xbc800000, v50
	v_fmamk_f32 v136, v131, 0xbc800000, v48
	v_mul_f32_e32 v137, v137, v137
	v_mul_f32_e32 v135, v135, v135
	v_fmac_f32_e32 v137, v136, v136
	v_fmac_f32_e32 v135, v134, v134
	v_add_f32_e32 v134, v137, v135
	v_fmamk_f32 v135, v131, 0xbc800000, v19
	v_fmamk_f32 v137, v131, 0xbc800000, v17
	v_add_f32_e32 v133, v133, v134
	v_fmamk_f32 v134, v131, 0xbc800000, v18
	v_fmamk_f32 v136, v131, 0xbc800000, v16
	v_mul_f32_e32 v137, v137, v137
	v_mul_f32_e32 v135, v135, v135
	v_fmac_f32_e32 v137, v136, v136
	v_fmac_f32_e32 v135, v134, v134
	v_add_f32_e32 v134, v137, v135
	v_fmamk_f32 v135, v131, 0xbc800000, v3
	v_fmamk_f32 v137, v131, 0xbc800000, v1
	v_add_f32_e32 v133, v134, v133
	v_fmamk_f32 v134, v131, 0xbc800000, v2
	v_fmamk_f32 v136, v131, 0xbc800000, v0
	v_mul_f32_e32 v137, v137, v137
	v_mul_f32_e32 v135, v135, v135
	v_fmac_f32_e32 v137, v136, v136
	v_fmac_f32_e32 v135, v134, v134
	v_add_f32_e32 v134, v137, v135
	v_add_f32_e32 v133, v134, v133
	v_mov_b32_e32 v218, v133
	v_mov_b32_e32 v134, v133
	s_nop 1
	v_permlane16_swap_b32_e32 v218, v134
	s_waitcnt lgkmcnt(0)
	v_add_f32_e32 v133, v218, v134
	v_mov_b32_e32 v218, v133
	v_mov_b32_e32 v134, v133
	s_nop 1
	v_permlane32_swap_b32_e32 v218, v134
	s_and_saveexec_b64 s[4:5], vcc
	s_cbranch_execz .LBB0_54
	s_lshl_b32 s9, s26, 11
	s_add_i32 s9, s8, s9
	v_mul_f32_e32 v136, 0x3c800000, v131
	v_lshl_add_u32 v131, v144, 5, s9
	s_waitcnt lgkmcnt(0)
	v_add_f32_e32 v137, v218, v134
	ds_write_b64 v131, v[136:137] offset:1536
.LBB0_54:
	s_or_b64 exec, exec, s[4:5]
	s_waitcnt lgkmcnt(0)
	v_mov_b32_e32 v134, v125
	v_mov_b32_e32 v135, v126
	v_mov_b32_e32 v136, v124
	v_mov_b32_e32 v137, v127
	v_pk_add_f32 v[134:135], v[134:135], v[136:137]
	v_mov_b32_e32 v136, v109
	v_mov_b32_e32 v137, v110
	v_mov_b32_e32 v140, v108
	v_mov_b32_e32 v141, v111
	v_pk_add_f32 v[136:137], v[136:137], v[140:141]
	v_add_f32_e32 v131, v134, v135
	v_pk_add_f32 v[136:137], v[136:137], v[136:137] op_sel_hi:[0,1]
	v_add_f32_e32 v135, 0, v131
	v_add_f32_e32 v141, v76, v77
	v_add_f32_e32 v143, v78, v79
	v_mov_b32_e32 v140, v44
	v_mov_b32_e32 v142, v45
	v_mov_b32_e32 v136, v46
	v_mov_b32_e32 v134, v47
	v_pk_add_f32 v[140:141], v[140:141], v[142:143]
	v_pk_add_f32 v[134:135], v[136:137], v[134:135]
	s_nop 0
	v_pk_add_f32 v[134:135], v[140:141], v[134:135]
	s_nop 0
	v_add_f32_e32 v131, v134, v135
	v_mov_b32_e32 v218, v131
	v_mov_b32_e32 v133, v131
	s_nop 1
	v_permlane16_swap_b32_e32 v218, v133
	s_waitcnt lgkmcnt(0)
	v_add_f32_e32 v131, v218, v133
	v_mov_b32_e32 v218, v131
	v_mov_b32_e32 v133, v131
	s_nop 1
	v_permlane32_swap_b32_e32 v218, v133
	s_waitcnt lgkmcnt(0)
	v_add_f32_e32 v131, v218, v133
	v_fmamk_f32 v134, v131, 0xbc800000, v127
	v_fmamk_f32 v136, v131, 0xbc800000, v125
	v_fmamk_f32 v133, v131, 0xbc800000, v126
	v_fmamk_f32 v135, v131, 0xbc800000, v124
	v_mul_f32_e32 v136, v136, v136
	v_mul_f32_e32 v134, v134, v134
	v_fmac_f32_e32 v136, v135, v135
	v_fmac_f32_e32 v134, v133, v133
	v_fmamk_f32 v135, v131, 0xbc800000, v111
	v_fmamk_f32 v137, v131, 0xbc800000, v109
	v_add_f32_e32 v133, v136, v134
	v_fmamk_f32 v134, v131, 0xbc800000, v110
	v_fmamk_f32 v136, v131, 0xbc800000, v108
	v_mul_f32_e32 v137, v137, v137
	v_mul_f32_e32 v135, v135, v135
	v_fmac_f32_e32 v137, v136, v136
	v_fmac_f32_e32 v135, v134, v134
	v_add_f32_e32 v134, v137, v135
	v_fmamk_f32 v135, v131, 0xbc800000, v79
	v_fmamk_f32 v137, v131, 0xbc800000, v77
	v_add_f32_e32 v133, v133, v134
	v_fmamk_f32 v134, v131, 0xbc800000, v78
	v_fmamk_f32 v136, v131, 0xbc800000, v76
	v_mul_f32_e32 v137, v137, v137
	v_mul_f32_e32 v135, v135, v135
	v_fmac_f32_e32 v137, v136, v136
	v_fmac_f32_e32 v135, v134, v134
	v_add_f32_e32 v134, v137, v135
	v_fmamk_f32 v135, v131, 0xbc800000, v47
	v_fmamk_f32 v137, v131, 0xbc800000, v45
	v_add_f32_e32 v133, v134, v133
	v_fmamk_f32 v134, v131, 0xbc800000, v46
	v_fmamk_f32 v136, v131, 0xbc800000, v44
	v_mul_f32_e32 v137, v137, v137
	v_mul_f32_e32 v135, v135, v135
	v_fmac_f32_e32 v137, v136, v136
	v_fmac_f32_e32 v135, v134, v134
	v_add_f32_e32 v134, v137, v135
	v_add_f32_e32 v133, v134, v133
	v_mov_b32_e32 v218, v133
	v_mov_b32_e32 v134, v133
	s_nop 1
	v_permlane16_swap_b32_e32 v218, v134
	s_waitcnt lgkmcnt(0)
	v_add_f32_e32 v133, v218, v134
	v_mov_b32_e32 v218, v133
	v_mov_b32_e32 v134, v133
	s_nop 1
	v_permlane32_swap_b32_e32 v218, v134
	s_and_saveexec_b64 s[4:5], vcc
	s_cbranch_execz .LBB0_56
	s_lshl_b32 s9, s26, 11
	s_add_i32 s9, s8, s9
	v_mul_f32_e32 v136, 0x3c800000, v131
	v_lshl_add_u32 v131, v144, 5, s9
	s_waitcnt lgkmcnt(0)
	v_add_f32_e32 v137, v218, v134
	ds_write_b64 v131, v[136:137] offset:4096
.LBB0_56:
	s_or_b64 exec, exec, s[4:5]
	s_waitcnt lgkmcnt(0)
	v_mov_b32_e32 v134, v121
	v_mov_b32_e32 v135, v122
	v_mov_b32_e32 v136, v120
	v_mov_b32_e32 v137, v123
	v_pk_add_f32 v[134:135], v[134:135], v[136:137]
	v_mov_b32_e32 v136, v105
	v_mov_b32_e32 v137, v106
	v_mov_b32_e32 v140, v104
	v_mov_b32_e32 v141, v107
	v_pk_add_f32 v[136:137], v[136:137], v[140:141]
	v_add_f32_e32 v131, v134, v135
	v_pk_add_f32 v[136:137], v[136:137], v[136:137] op_sel_hi:[0,1]
	v_add_f32_e32 v135, 0, v131
	v_add_f32_e32 v141, v72, v73
	v_add_f32_e32 v143, v74, v75
	v_mov_b32_e32 v140, v40
	v_mov_b32_e32 v142, v41
	v_mov_b32_e32 v136, v42
	v_mov_b32_e32 v134, v43
	v_pk_add_f32 v[140:141], v[140:141], v[142:143]
	v_pk_add_f32 v[134:135], v[136:137], v[134:135]
	s_nop 0
	v_pk_add_f32 v[134:135], v[140:141], v[134:135]
	s_nop 0
	v_add_f32_e32 v131, v134, v135
	v_mov_b32_e32 v218, v131
	v_mov_b32_e32 v133, v131
	s_nop 1
	v_permlane16_swap_b32_e32 v218, v133
	s_waitcnt lgkmcnt(0)
	v_add_f32_e32 v131, v218, v133
	v_mov_b32_e32 v218, v131
	v_mov_b32_e32 v133, v131
	s_nop 1
	v_permlane32_swap_b32_e32 v218, v133
	s_waitcnt lgkmcnt(0)
	v_add_f32_e32 v131, v218, v133
	v_fmamk_f32 v134, v131, 0xbc800000, v123
	v_fmamk_f32 v136, v131, 0xbc800000, v121
	v_fmamk_f32 v133, v131, 0xbc800000, v122
	v_fmamk_f32 v135, v131, 0xbc800000, v120
	v_mul_f32_e32 v136, v136, v136
	v_mul_f32_e32 v134, v134, v134
	v_fmac_f32_e32 v136, v135, v135
	v_fmac_f32_e32 v134, v133, v133
	v_fmamk_f32 v135, v131, 0xbc800000, v107
	v_fmamk_f32 v137, v131, 0xbc800000, v105
	v_add_f32_e32 v133, v136, v134
	v_fmamk_f32 v134, v131, 0xbc800000, v106
	v_fmamk_f32 v136, v131, 0xbc800000, v104
	v_mul_f32_e32 v137, v137, v137
	v_mul_f32_e32 v135, v135, v135
	v_fmac_f32_e32 v137, v136, v136
	v_fmac_f32_e32 v135, v134, v134
	v_add_f32_e32 v134, v137, v135
	v_fmamk_f32 v135, v131, 0xbc800000, v75
	v_fmamk_f32 v137, v131, 0xbc800000, v73
	v_add_f32_e32 v133, v133, v134
	v_fmamk_f32 v134, v131, 0xbc800000, v74
	v_fmamk_f32 v136, v131, 0xbc800000, v72
	v_mul_f32_e32 v137, v137, v137
	v_mul_f32_e32 v135, v135, v135
	v_fmac_f32_e32 v137, v136, v136
	v_fmac_f32_e32 v135, v134, v134
	v_add_f32_e32 v134, v137, v135
	v_fmamk_f32 v135, v131, 0xbc800000, v43
	v_fmamk_f32 v137, v131, 0xbc800000, v41
	v_add_f32_e32 v133, v134, v133
	v_fmamk_f32 v134, v131, 0xbc800000, v42
	v_fmamk_f32 v136, v131, 0xbc800000, v40
	v_mul_f32_e32 v137, v137, v137
	v_mul_f32_e32 v135, v135, v135
	v_fmac_f32_e32 v137, v136, v136
	v_fmac_f32_e32 v135, v134, v134
	v_add_f32_e32 v134, v137, v135
	v_add_f32_e32 v133, v134, v133
	v_mov_b32_e32 v218, v133
	v_mov_b32_e32 v134, v133
	s_nop 1
	v_permlane16_swap_b32_e32 v218, v134
	s_waitcnt lgkmcnt(0)
	v_add_f32_e32 v133, v218, v134
	v_mov_b32_e32 v218, v133
	v_mov_b32_e32 v134, v133
	s_nop 1
	v_permlane32_swap_b32_e32 v218, v134
	s_and_saveexec_b64 s[4:5], vcc
	s_cbranch_execz .LBB0_58
	s_lshl_b32 s9, s26, 11
	s_add_i32 s9, s8, s9
	v_mul_f32_e32 v136, 0x3c800000, v131
	v_lshl_add_u32 v131, v144, 5, s9
	s_waitcnt lgkmcnt(0)
	v_add_f32_e32 v137, v218, v134
	ds_write_b64 v131, v[136:137] offset:4608
.LBB0_58:
	s_or_b64 exec, exec, s[4:5]
	s_waitcnt lgkmcnt(0)
	v_mov_b32_e32 v134, v117
	v_mov_b32_e32 v135, v118
	v_mov_b32_e32 v136, v116
	v_mov_b32_e32 v137, v119
	v_pk_add_f32 v[134:135], v[134:135], v[136:137]
	v_mov_b32_e32 v136, v101
	v_mov_b32_e32 v137, v102
	v_mov_b32_e32 v140, v100
	v_mov_b32_e32 v141, v103
	v_pk_add_f32 v[136:137], v[136:137], v[140:141]
	v_add_f32_e32 v131, v134, v135
	v_pk_add_f32 v[136:137], v[136:137], v[136:137] op_sel_hi:[0,1]
	v_add_f32_e32 v135, 0, v131
	v_add_f32_e32 v141, v68, v69
	v_add_f32_e32 v143, v70, v71
	v_mov_b32_e32 v140, v36
	v_mov_b32_e32 v142, v37
	v_mov_b32_e32 v136, v38
	v_mov_b32_e32 v134, v39
	v_pk_add_f32 v[140:141], v[140:141], v[142:143]
	v_pk_add_f32 v[134:135], v[136:137], v[134:135]
	s_nop 0
	v_pk_add_f32 v[134:135], v[140:141], v[134:135]
	s_nop 0
	v_add_f32_e32 v131, v134, v135
	v_mov_b32_e32 v218, v131
	v_mov_b32_e32 v133, v131
	s_nop 1
	v_permlane16_swap_b32_e32 v218, v133
	s_waitcnt lgkmcnt(0)
	v_add_f32_e32 v131, v218, v133
	v_mov_b32_e32 v218, v131
	v_mov_b32_e32 v133, v131
	s_nop 1
	v_permlane32_swap_b32_e32 v218, v133
	s_waitcnt lgkmcnt(0)
	v_add_f32_e32 v131, v218, v133
	v_fmamk_f32 v134, v131, 0xbc800000, v119
	v_fmamk_f32 v136, v131, 0xbc800000, v117
	v_fmamk_f32 v133, v131, 0xbc800000, v118
	v_fmamk_f32 v135, v131, 0xbc800000, v116
	v_mul_f32_e32 v136, v136, v136
	v_mul_f32_e32 v134, v134, v134
	v_fmac_f32_e32 v136, v135, v135
	v_fmac_f32_e32 v134, v133, v133
	v_fmamk_f32 v135, v131, 0xbc800000, v103
	v_fmamk_f32 v137, v131, 0xbc800000, v101
	v_add_f32_e32 v133, v136, v134
	v_fmamk_f32 v134, v131, 0xbc800000, v102
	v_fmamk_f32 v136, v131, 0xbc800000, v100
	v_mul_f32_e32 v137, v137, v137
	v_mul_f32_e32 v135, v135, v135
	v_fmac_f32_e32 v137, v136, v136
	v_fmac_f32_e32 v135, v134, v134
	v_add_f32_e32 v134, v137, v135
	v_fmamk_f32 v135, v131, 0xbc800000, v71
	v_fmamk_f32 v137, v131, 0xbc800000, v69
	v_add_f32_e32 v133, v133, v134
	v_fmamk_f32 v134, v131, 0xbc800000, v70
	v_fmamk_f32 v136, v131, 0xbc800000, v68
	v_mul_f32_e32 v137, v137, v137
	v_mul_f32_e32 v135, v135, v135
	v_fmac_f32_e32 v137, v136, v136
	v_fmac_f32_e32 v135, v134, v134
	v_add_f32_e32 v134, v137, v135
	v_fmamk_f32 v135, v131, 0xbc800000, v39
	v_fmamk_f32 v137, v131, 0xbc800000, v37
	v_add_f32_e32 v133, v134, v133
	v_fmamk_f32 v134, v131, 0xbc800000, v38
	v_fmamk_f32 v136, v131, 0xbc800000, v36
	v_mul_f32_e32 v137, v137, v137
	v_mul_f32_e32 v135, v135, v135
	v_fmac_f32_e32 v137, v136, v136
	v_fmac_f32_e32 v135, v134, v134
	v_add_f32_e32 v134, v137, v135
	v_add_f32_e32 v133, v134, v133
	v_mov_b32_e32 v218, v133
	v_mov_b32_e32 v134, v133
	s_nop 1
	v_permlane16_swap_b32_e32 v218, v134
	s_waitcnt lgkmcnt(0)
	v_add_f32_e32 v133, v218, v134
	v_mov_b32_e32 v218, v133
	v_mov_b32_e32 v134, v133
	s_nop 1
	v_permlane32_swap_b32_e32 v218, v134
	s_and_saveexec_b64 s[4:5], vcc
	s_cbranch_execz .LBB0_60
	s_lshl_b32 s9, s26, 11
	s_add_i32 s9, s8, s9
	v_mul_f32_e32 v136, 0x3c800000, v131
	v_lshl_add_u32 v131, v144, 5, s9
	s_waitcnt lgkmcnt(0)
	v_add_f32_e32 v137, v218, v134
	ds_write_b64 v131, v[136:137] offset:5120
.LBB0_60:
	s_or_b64 exec, exec, s[4:5]
	s_waitcnt lgkmcnt(0)
	v_mov_b32_e32 v134, v113
	v_mov_b32_e32 v135, v114
	v_mov_b32_e32 v136, v112
	v_mov_b32_e32 v137, v115
	v_pk_add_f32 v[134:135], v[134:135], v[136:137]
	v_mov_b32_e32 v136, v97
	v_mov_b32_e32 v137, v98
	v_mov_b32_e32 v140, v96
	v_mov_b32_e32 v141, v99
	v_pk_add_f32 v[136:137], v[136:137], v[140:141]
	v_add_f32_e32 v131, v134, v135
	v_pk_add_f32 v[136:137], v[136:137], v[136:137] op_sel_hi:[0,1]
	v_add_f32_e32 v135, 0, v131
	v_add_f32_e32 v141, v64, v65
	v_add_f32_e32 v143, v66, v67
	v_mov_b32_e32 v140, v32
	v_mov_b32_e32 v142, v33
	v_mov_b32_e32 v136, v34
	v_mov_b32_e32 v134, v35
	v_pk_add_f32 v[140:141], v[140:141], v[142:143]
	v_pk_add_f32 v[134:135], v[136:137], v[134:135]
	s_nop 0
	v_pk_add_f32 v[134:135], v[140:141], v[134:135]
	s_nop 0
	v_add_f32_e32 v131, v134, v135
	v_mov_b32_e32 v218, v131
	v_mov_b32_e32 v133, v131
	s_nop 1
	v_permlane16_swap_b32_e32 v218, v133
	s_waitcnt lgkmcnt(0)
	v_add_f32_e32 v131, v218, v133
	v_mov_b32_e32 v218, v131
	v_mov_b32_e32 v133, v131
	s_nop 1
	v_permlane32_swap_b32_e32 v218, v133
	s_waitcnt lgkmcnt(0)
	v_add_f32_e32 v131, v218, v133
	v_fmamk_f32 v134, v131, 0xbc800000, v115
	v_fmamk_f32 v136, v131, 0xbc800000, v113
	v_fmamk_f32 v133, v131, 0xbc800000, v114
	v_fmamk_f32 v135, v131, 0xbc800000, v112
	v_mul_f32_e32 v136, v136, v136
	v_mul_f32_e32 v134, v134, v134
	v_fmac_f32_e32 v136, v135, v135
	v_fmac_f32_e32 v134, v133, v133
	v_fmamk_f32 v135, v131, 0xbc800000, v99
	v_fmamk_f32 v137, v131, 0xbc800000, v97
	v_add_f32_e32 v133, v136, v134
	v_fmamk_f32 v134, v131, 0xbc800000, v98
	v_fmamk_f32 v136, v131, 0xbc800000, v96
	v_mul_f32_e32 v137, v137, v137
	v_mul_f32_e32 v135, v135, v135
	v_fmac_f32_e32 v137, v136, v136
	v_fmac_f32_e32 v135, v134, v134
	v_add_f32_e32 v134, v137, v135
	v_fmamk_f32 v135, v131, 0xbc800000, v67
	v_fmamk_f32 v137, v131, 0xbc800000, v65
	v_add_f32_e32 v133, v133, v134
	v_fmamk_f32 v134, v131, 0xbc800000, v66
	v_fmamk_f32 v136, v131, 0xbc800000, v64
	v_mul_f32_e32 v137, v137, v137
	v_mul_f32_e32 v135, v135, v135
	v_fmac_f32_e32 v137, v136, v136
	v_fmac_f32_e32 v135, v134, v134
	v_add_f32_e32 v134, v137, v135
	v_fmamk_f32 v135, v131, 0xbc800000, v35
	v_fmamk_f32 v137, v131, 0xbc800000, v33
	v_add_f32_e32 v133, v134, v133
	v_fmamk_f32 v134, v131, 0xbc800000, v34
	v_fmamk_f32 v136, v131, 0xbc800000, v32
	v_mul_f32_e32 v137, v137, v137
	v_mul_f32_e32 v135, v135, v135
	v_fmac_f32_e32 v137, v136, v136
	v_fmac_f32_e32 v135, v134, v134
	v_add_f32_e32 v134, v137, v135
	v_add_f32_e32 v133, v134, v133
	v_mov_b32_e32 v218, v133
	v_mov_b32_e32 v130, v133
	s_nop 1
	v_permlane16_swap_b32_e32 v218, v130
	s_waitcnt lgkmcnt(0)
	v_add_f32_e32 v130, v218, v130
	v_mov_b32_e32 v218, v130
	v_mov_b32_e32 v128, v130
	s_nop 1
	v_permlane32_swap_b32_e32 v218, v128
	s_and_saveexec_b64 s[4:5], vcc
	s_cbranch_execz .LBB0_62
	s_lshl_b32 s9, s26, 11
	s_add_i32 s8, s8, s9
	v_mul_f32_e32 v134, 0x3c800000, v131
	v_lshl_add_u32 v131, v144, 5, s8
	s_waitcnt lgkmcnt(0)
	v_add_f32_e32 v135, v218, v128
	ds_write_b64 v131, v[134:135] offset:5632

.LBB0_127:
	v_readlane_b32 s4, v253, 9
	s_add_i32 s4, s4, 3
	v_readlane_b32 s36, v254, 51
	v_readlane_b32 s5, v253, 10
	s_cmp_lt_u32 s4, 9
	v_readlane_b32 s37, v254, 52
	s_cselect_b32 s5, s37, s1
	s_cselect_b32 s4, s36, s0
	s_lshl_b32 s8, s28, 5
	s_lshl_b32 s9, s6, 8
	s_or_b32 s8, s9, s8
	v_lshrrev_b32_e32 v128, 2, v145
	v_and_or_b32 v138, v128, 12, s8
	s_lshl_b32 s8, s27, 8
	s_add_i32 s9, s8, s24
	v_or_b32_e32 v146, s9, v144
	s_barrier
	s_mov_b32 s10, 0x3fb504f3
	v_lshl_add_u32 v128, v146, 11, v138
	v_lshl_add_u64 v[130:131], v[128:129], 2, s[4:5]
	global_load_dwordx4 v[134:137], v[130:131], off nt
	global_load_dwordx4 v[140:143], v[130:131], off offset:64 nt
	global_load_dwordx4 v[148:151], v[130:131], off offset:512 nt
	global_load_dwordx4 v[152:155], v[130:131], off offset:576 nt
	v_add_u32_e32 v130, 0x8000, v128
	v_mov_b32_e32 v131, v129
	v_lshl_add_u64 v[130:131], v[130:131], 2, s[4:5]
	global_load_dwordx4 v[156:159], v[130:131], off nt
	global_load_dwordx4 v[160:163], v[130:131], off offset:64 nt
	global_load_dwordx4 v[164:167], v[130:131], off offset:512 nt
	global_load_dwordx4 v[168:171], v[130:131], off offset:576 nt
	v_add_u32_e32 v130, 0x10000, v128
	v_mov_b32_e32 v131, v129
	v_lshl_add_u64 v[130:131], v[130:131], 2, s[4:5]
	global_load_dwordx4 v[172:175], v[130:131], off nt
	global_load_dwordx4 v[176:179], v[130:131], off offset:64 nt
	global_load_dwordx4 v[180:183], v[130:131], off offset:512 nt
	global_load_dwordx4 v[184:187], v[130:131], off offset:576 nt
	v_add_u32_e32 v130, 0x18000, v128
	v_mov_b32_e32 v131, v129
	v_lshl_add_u64 v[130:131], v[130:131], 2, s[4:5]
	global_load_dwordx4 v[188:191], v[130:131], off nt
	global_load_dwordx4 v[192:195], v[130:131], off offset:64 nt
	global_load_dwordx4 v[196:199], v[130:131], off offset:512 nt
	global_load_dwordx4 v[200:203], v[130:131], off offset:576 nt
	v_add_u32_e32 v130, 0x40000, v128
	v_mov_b32_e32 v131, v129
	v_lshl_add_u64 v[130:131], v[130:131], 2, s[4:5]
	v_and_b32_e32 v132, 63, v145
	v_cmp_gt_u32_e32 vcc, 16, v132
	v_readlane_b32 s38, v254, 53
	v_readlane_b32 s39, v254, 54
	v_readlane_b32 s40, v254, 55
	v_readlane_b32 s41, v254, 56
	v_readlane_b32 s42, v254, 57
	v_readlane_b32 s43, v254, 58
	v_readlane_b32 s44, v254, 59
	v_readlane_b32 s45, v254, 60
	v_readlane_b32 s46, v254, 61
	v_readlane_b32 s47, v254, 62
	v_readlane_b32 s48, v254, 63
	v_readlane_b32 s49, v255, 0
	v_readlane_b32 s50, v255, 1
	v_readlane_b32 s51, v255, 2
	s_waitcnt vmcnt(0)
	v_pk_fma_f32 v[94:95], v[136:137], s[10:11], v[94:95] op_sel_hi:[1,0,1]
	v_pk_fma_f32 v[92:93], v[134:135], s[10:11], v[92:93] op_sel_hi:[1,0,1]
	v_pk_fma_f32 v[62:63], v[142:143], s[10:11], v[62:63] op_sel_hi:[1,0,1]
	v_pk_fma_f32 v[60:61], v[140:141], s[10:11], v[60:61] op_sel_hi:[1,0,1]
	v_pk_fma_f32 v[30:31], v[150:151], s[10:11], v[30:31] op_sel_hi:[1,0,1]
	v_pk_fma_f32 v[28:29], v[148:149], s[10:11], v[28:29] op_sel_hi:[1,0,1]
	v_pk_fma_f32 v[14:15], v[154:155], s[10:11], v[14:15] op_sel_hi:[1,0,1]
	v_pk_fma_f32 v[12:13], v[152:153], s[10:11], v[12:13] op_sel_hi:[1,0,1]
	v_pk_fma_f32 v[90:91], v[158:159], s[10:11], v[90:91] op_sel_hi:[1,0,1]
	v_pk_fma_f32 v[88:89], v[156:157], s[10:11], v[88:89] op_sel_hi:[1,0,1]
	v_pk_fma_f32 v[58:59], v[162:163], s[10:11], v[58:59] op_sel_hi:[1,0,1]
	v_pk_fma_f32 v[56:57], v[160:161], s[10:11], v[56:57] op_sel_hi:[1,0,1]
	v_pk_fma_f32 v[26:27], v[166:167], s[10:11], v[26:27] op_sel_hi:[1,0,1]
	v_pk_fma_f32 v[24:25], v[164:165], s[10:11], v[24:25] op_sel_hi:[1,0,1]
	v_pk_fma_f32 v[10:11], v[170:171], s[10:11], v[10:11] op_sel_hi:[1,0,1]
	v_pk_fma_f32 v[8:9], v[168:169], s[10:11], v[8:9] op_sel_hi:[1,0,1]
	v_pk_fma_f32 v[86:87], v[174:175], s[10:11], v[86:87] op_sel_hi:[1,0,1]
	v_pk_fma_f32 v[84:85], v[172:173], s[10:11], v[84:85] op_sel_hi:[1,0,1]
	v_pk_fma_f32 v[54:55], v[178:179], s[10:11], v[54:55] op_sel_hi:[1,0,1]
	v_pk_fma_f32 v[52:53], v[176:177], s[10:11], v[52:53] op_sel_hi:[1,0,1]
	v_pk_fma_f32 v[22:23], v[182:183], s[10:11], v[22:23] op_sel_hi:[1,0,1]
	v_pk_fma_f32 v[20:21], v[180:181], s[10:11], v[20:21] op_sel_hi:[1,0,1]
	v_pk_fma_f32 v[6:7], v[186:187], s[10:11], v[6:7] op_sel_hi:[1,0,1]
	v_pk_fma_f32 v[4:5], v[184:185], s[10:11], v[4:5] op_sel_hi:[1,0,1]
	v_pk_fma_f32 v[82:83], v[190:191], s[10:11], v[82:83] op_sel_hi:[1,0,1]
	v_pk_fma_f32 v[80:81], v[188:189], s[10:11], v[80:81] op_sel_hi:[1,0,1]
	v_pk_fma_f32 v[50:51], v[194:195], s[10:11], v[50:51] op_sel_hi:[1,0,1]
	v_pk_fma_f32 v[48:49], v[192:193], s[10:11], v[48:49] op_sel_hi:[1,0,1]
	v_pk_fma_f32 v[18:19], v[198:199], s[10:11], v[18:19] op_sel_hi:[1,0,1]
	v_pk_fma_f32 v[16:17], v[196:197], s[10:11], v[16:17] op_sel_hi:[1,0,1]
	v_pk_fma_f32 v[2:3], v[202:203], s[10:11], v[2:3] op_sel_hi:[1,0,1]
	v_pk_fma_f32 v[0:1], v[200:201], s[10:11], v[0:1] op_sel_hi:[1,0,1]
	s_nop 0
	global_load_dwordx4 v[134:137], v[130:131], off nt
	global_load_dwordx4 v[140:143], v[130:131], off offset:64 nt
	global_load_dwordx4 v[148:151], v[130:131], off offset:512 nt
	global_load_dwordx4 v[152:155], v[130:131], off offset:576 nt
	v_add_u32_e32 v130, 0x48000, v128
	v_mov_b32_e32 v131, v129
	v_lshl_add_u64 v[130:131], v[130:131], 2, s[4:5]
	global_load_dwordx4 v[156:159], v[130:131], off nt
	global_load_dwordx4 v[160:163], v[130:131], off offset:64 nt
	global_load_dwordx4 v[164:167], v[130:131], off offset:512 nt
	global_load_dwordx4 v[168:171], v[130:131], off offset:576 nt
	v_add_u32_e32 v130, 0x50000, v128
	v_mov_b32_e32 v131, v129
	v_lshl_add_u64 v[130:131], v[130:131], 2, s[4:5]
	v_add_u32_e32 v128, 0x58000, v128
	global_load_dwordx4 v[172:175], v[130:131], off nt
	global_load_dwordx4 v[176:179], v[130:131], off offset:64 nt
	global_load_dwordx4 v[180:183], v[130:131], off offset:512 nt
	global_load_dwordx4 v[184:187], v[130:131], off offset:576 nt
	v_lshl_add_u64 v[130:131], v[128:129], 2, s[4:5]
	global_load_dwordx4 v[188:191], v[130:131], off nt
	global_load_dwordx4 v[192:195], v[130:131], off offset:64 nt
	global_load_dwordx4 v[196:199], v[130:131], off offset:512 nt
	global_load_dwordx4 v[200:203], v[130:131], off offset:576 nt
	v_lshlrev_b32_e32 v128, 2, v132
	v_xor_b32_e32 v130, 64, v128
	v_xor_b32_e32 v128, 0x80, v128
	s_lshl_b32 s4, s28, 3
	s_add_i32 s9, s4, 0
	s_waitcnt vmcnt(15)
	v_pk_fma_f32 v[126:127], v[136:137], s[10:11], v[126:127] op_sel_hi:[1,0,1]
	v_pk_fma_f32 v[124:125], v[134:135], s[10:11], v[124:125] op_sel_hi:[1,0,1]
	v_mov_b32_e32 v134, v93
	v_mov_b32_e32 v135, v94
	v_mov_b32_e32 v136, v92
	v_mov_b32_e32 v137, v95
	s_waitcnt vmcnt(14)
	v_pk_fma_f32 v[108:109], v[140:141], s[10:11], v[108:109] op_sel_hi:[1,0,1]
	v_pk_add_f32 v[134:135], v[134:135], v[136:137]
	v_mov_b32_e32 v136, v61
	v_mov_b32_e32 v137, v62
	v_mov_b32_e32 v140, v60
	v_mov_b32_e32 v141, v63
	v_pk_add_f32 v[136:137], v[136:137], v[140:141]
	v_add_f32_e32 v131, v134, v135
	v_pk_add_f32 v[136:137], v[136:137], v[136:137] op_sel_hi:[0,1]
	v_pk_fma_f32 v[110:111], v[142:143], s[10:11], v[110:111] op_sel_hi:[1,0,1]
	v_add_f32_e32 v135, 0, v131
	v_add_f32_e32 v141, v28, v29
	v_add_f32_e32 v143, v30, v31
	v_mov_b32_e32 v140, v12
	v_mov_b32_e32 v142, v13
	v_mov_b32_e32 v136, v14
	v_mov_b32_e32 v134, v15
	v_pk_add_f32 v[140:141], v[140:141], v[142:143]
	v_pk_add_f32 v[134:135], v[136:137], v[134:135]
	s_waitcnt vmcnt(13)
	v_pk_fma_f32 v[78:79], v[150:151], s[10:11], v[78:79] op_sel_hi:[1,0,1]
	v_pk_add_f32 v[134:135], v[140:141], v[134:135]
	v_pk_fma_f32 v[76:77], v[148:149], s[10:11], v[76:77] op_sel_hi:[1,0,1]
	v_add_f32_e32 v131, v134, v135
	v_mov_b32_e32 v218, v131
	v_mov_b32_e32 v133, v131
	s_nop 1
	v_permlane16_swap_b32_e32 v218, v133
	s_waitcnt vmcnt(12)
	v_pk_fma_f32 v[46:47], v[154:155], s[10:11], v[46:47] op_sel_hi:[1,0,1]
	v_pk_fma_f32 v[44:45], v[152:153], s[10:11], v[44:45] op_sel_hi:[1,0,1]
	s_waitcnt vmcnt(11)
	v_pk_fma_f32 v[122:123], v[158:159], s[10:11], v[122:123] op_sel_hi:[1,0,1]
	v_pk_fma_f32 v[120:121], v[156:157], s[10:11], v[120:121] op_sel_hi:[1,0,1]
	s_waitcnt lgkmcnt(0)
	v_add_f32_e32 v131, v218, v133
	v_mov_b32_e32 v218, v131
	v_mov_b32_e32 v133, v131
	s_nop 1
	v_permlane32_swap_b32_e32 v218, v133
	s_waitcnt vmcnt(10)
	v_pk_fma_f32 v[106:107], v[162:163], s[10:11], v[106:107] op_sel_hi:[1,0,1]
	v_pk_fma_f32 v[104:105], v[160:161], s[10:11], v[104:105] op_sel_hi:[1,0,1]
	s_waitcnt vmcnt(9)
	v_pk_fma_f32 v[74:75], v[166:167], s[10:11], v[74:75] op_sel_hi:[1,0,1]
	v_pk_fma_f32 v[72:73], v[164:165], s[10:11], v[72:73] op_sel_hi:[1,0,1]
	s_waitcnt lgkmcnt(0)
	v_add_f32_e32 v131, v218, v133
	v_fmamk_f32 v134, v131, 0xbc800000, v95
	v_fmamk_f32 v136, v131, 0xbc800000, v93
	v_fmamk_f32 v133, v131, 0xbc800000, v94
	v_fmamk_f32 v135, v131, 0xbc800000, v92
	v_mul_f32_e32 v136, v136, v136
	v_mul_f32_e32 v134, v134, v134
	v_fmac_f32_e32 v136, v135, v135
	v_fmac_f32_e32 v134, v133, v133
	v_fmamk_f32 v135, v131, 0xbc800000, v63
	v_fmamk_f32 v137, v131, 0xbc800000, v61
	v_add_f32_e32 v133, v136, v134
	v_fmamk_f32 v134, v131, 0xbc800000, v62
	v_fmamk_f32 v136, v131, 0xbc800000, v60
	v_mul_f32_e32 v137, v137, v137
	v_mul_f32_e32 v135, v135, v135
	v_fmac_f32_e32 v137, v136, v136
	v_fmac_f32_e32 v135, v134, v134
	v_add_f32_e32 v134, v137, v135
	v_fmamk_f32 v135, v131, 0xbc800000, v31
	v_fmamk_f32 v137, v131, 0xbc800000, v29
	v_add_f32_e32 v133, v133, v134
	v_fmamk_f32 v134, v131, 0xbc800000, v30
	v_fmamk_f32 v136, v131, 0xbc800000, v28
	v_mul_f32_e32 v137, v137, v137
	v_mul_f32_e32 v135, v135, v135
	v_fmac_f32_e32 v137, v136, v136
	v_fmac_f32_e32 v135, v134, v134
	v_add_f32_e32 v134, v137, v135
	v_fmamk_f32 v135, v131, 0xbc800000, v15
	v_fmamk_f32 v137, v131, 0xbc800000, v13
	v_add_f32_e32 v133, v134, v133
	v_fmamk_f32 v134, v131, 0xbc800000, v14
	v_fmamk_f32 v136, v131, 0xbc800000, v12
	v_mul_f32_e32 v137, v137, v137
	v_mul_f32_e32 v135, v135, v135
	v_fmac_f32_e32 v137, v136, v136
	v_fmac_f32_e32 v135, v134, v134
	v_add_f32_e32 v134, v137, v135
	v_add_f32_e32 v133, v134, v133
	v_mov_b32_e32 v218, v133
	v_mov_b32_e32 v134, v133
	s_nop 1
	v_permlane16_swap_b32_e32 v218, v134
	s_waitcnt vmcnt(8)
	v_pk_fma_f32 v[42:43], v[170:171], s[10:11], v[42:43] op_sel_hi:[1,0,1]
	v_pk_fma_f32 v[40:41], v[168:169], s[10:11], v[40:41] op_sel_hi:[1,0,1]
	s_waitcnt vmcnt(7)
	v_pk_fma_f32 v[118:119], v[174:175], s[10:11], v[118:119] op_sel_hi:[1,0,1]
	v_pk_fma_f32 v[116:117], v[172:173], s[10:11], v[116:117] op_sel_hi:[1,0,1]
	s_waitcnt lgkmcnt(0)
	v_add_f32_e32 v133, v218, v134
	v_mov_b32_e32 v218, v133
	v_mov_b32_e32 v134, v133
	s_nop 1
	v_permlane32_swap_b32_e32 v218, v134
	s_waitcnt vmcnt(6)
	v_pk_fma_f32 v[102:103], v[178:179], s[10:11], v[102:103] op_sel_hi:[1,0,1]
	v_pk_fma_f32 v[100:101], v[176:177], s[10:11], v[100:101] op_sel_hi:[1,0,1]
	s_waitcnt vmcnt(5)
	v_pk_fma_f32 v[70:71], v[182:183], s[10:11], v[70:71] op_sel_hi:[1,0,1]
	v_pk_fma_f32 v[68:69], v[180:181], s[10:11], v[68:69] op_sel_hi:[1,0,1]
	s_waitcnt vmcnt(4)
	v_pk_fma_f32 v[38:39], v[186:187], s[10:11], v[38:39] op_sel_hi:[1,0,1]
	v_pk_fma_f32 v[36:37], v[184:185], s[10:11], v[36:37] op_sel_hi:[1,0,1]
	s_waitcnt vmcnt(3)
	v_pk_fma_f32 v[114:115], v[190:191], s[10:11], v[114:115] op_sel_hi:[1,0,1]
	v_pk_fma_f32 v[112:113], v[188:189], s[10:11], v[112:113] op_sel_hi:[1,0,1]
	s_waitcnt vmcnt(2)
	v_pk_fma_f32 v[98:99], v[194:195], s[10:11], v[98:99] op_sel_hi:[1,0,1]
	v_pk_fma_f32 v[96:97], v[192:193], s[10:11], v[96:97] op_sel_hi:[1,0,1]
	s_waitcnt vmcnt(1)
	v_pk_fma_f32 v[66:67], v[198:199], s[10:11], v[66:67] op_sel_hi:[1,0,1]
	v_pk_fma_f32 v[64:65], v[196:197], s[10:11], v[64:65] op_sel_hi:[1,0,1]
	s_waitcnt vmcnt(0)
	v_pk_fma_f32 v[34:35], v[202:203], s[10:11], v[34:35] op_sel_hi:[1,0,1]
	v_pk_fma_f32 v[32:33], v[200:201], s[10:11], v[32:33] op_sel_hi:[1,0,1]
	s_nop 0
	s_and_saveexec_b64 s[4:5], vcc
	v_readlane_b32 s30, v255, 3
	v_readlane_b32 s31, v255, 4
	s_cbranch_execz .LBB0_129
	s_lshl_b32 s10, s26, 11
	s_add_i32 s10, s9, s10
	v_mul_f32_e32 v136, 0x3c800000, v131
	v_lshl_add_u32 v131, v144, 5, s10
	s_waitcnt lgkmcnt(0)
	v_add_f32_e32 v137, v218, v134
	ds_write_b64 v131, v[136:137]
.LBB0_129:
	s_or_b64 exec, exec, s[4:5]
	s_waitcnt lgkmcnt(0)
	v_mov_b32_e32 v134, v89
	v_mov_b32_e32 v135, v90
	v_mov_b32_e32 v136, v88
	v_mov_b32_e32 v137, v91
	v_pk_add_f32 v[134:135], v[134:135], v[136:137]
	v_mov_b32_e32 v136, v57
	v_mov_b32_e32 v137, v58
	v_mov_b32_e32 v140, v56
	v_mov_b32_e32 v141, v59
	v_pk_add_f32 v[136:137], v[136:137], v[140:141]
	v_add_f32_e32 v131, v134, v135
	v_pk_add_f32 v[136:137], v[136:137], v[136:137] op_sel_hi:[0,1]
	v_add_f32_e32 v135, 0, v131
	v_add_f32_e32 v141, v24, v25
	v_add_f32_e32 v143, v26, v27
	v_mov_b32_e32 v140, v8
	v_mov_b32_e32 v142, v9
	v_mov_b32_e32 v136, v10
	v_mov_b32_e32 v134, v11
	v_pk_add_f32 v[140:141], v[140:141], v[142:143]
	v_pk_add_f32 v[134:135], v[136:137], v[134:135]
	s_nop 0
	v_pk_add_f32 v[134:135], v[140:141], v[134:135]
	s_nop 0
	v_add_f32_e32 v131, v134, v135
	v_mov_b32_e32 v218, v131
	v_mov_b32_e32 v133, v131
	s_nop 1
	v_permlane16_swap_b32_e32 v218, v133
	s_waitcnt lgkmcnt(0)
	v_add_f32_e32 v131, v218, v133
	v_mov_b32_e32 v218, v131
	v_mov_b32_e32 v133, v131
	s_nop 1
	v_permlane32_swap_b32_e32 v218, v133
	s_waitcnt lgkmcnt(0)
	v_add_f32_e32 v131, v218, v133
	v_fmamk_f32 v134, v131, 0xbc800000, v91
	v_fmamk_f32 v136, v131, 0xbc800000, v89
	v_fmamk_f32 v133, v131, 0xbc800000, v90
	v_fmamk_f32 v135, v131, 0xbc800000, v88
	v_mul_f32_e32 v136, v136, v136
	v_mul_f32_e32 v134, v134, v134
	v_fmac_f32_e32 v136, v135, v135
	v_fmac_f32_e32 v134, v133, v133
	v_fmamk_f32 v135, v131, 0xbc800000, v59
	v_fmamk_f32 v137, v131, 0xbc800000, v57
	v_add_f32_e32 v133, v136, v134
	v_fmamk_f32 v134, v131, 0xbc800000, v58
	v_fmamk_f32 v136, v131, 0xbc800000, v56
	v_mul_f32_e32 v137, v137, v137
	v_mul_f32_e32 v135, v135, v135
	v_fmac_f32_e32 v137, v136, v136
	v_fmac_f32_e32 v135, v134, v134
	v_add_f32_e32 v134, v137, v135
	v_fmamk_f32 v135, v131, 0xbc800000, v27
	v_fmamk_f32 v137, v131, 0xbc800000, v25
	v_add_f32_e32 v133, v133, v134
	v_fmamk_f32 v134, v131, 0xbc800000, v26
	v_fmamk_f32 v136, v131, 0xbc800000, v24
	v_mul_f32_e32 v137, v137, v137
	v_mul_f32_e32 v135, v135, v135
	v_fmac_f32_e32 v137, v136, v136
	v_fmac_f32_e32 v135, v134, v134
	v_add_f32_e32 v134, v137, v135
	v_fmamk_f32 v135, v131, 0xbc800000, v11
	v_fmamk_f32 v137, v131, 0xbc800000, v9
	v_add_f32_e32 v133, v134, v133
	v_fmamk_f32 v134, v131, 0xbc800000, v10
	v_fmamk_f32 v136, v131, 0xbc800000, v8
	v_mul_f32_e32 v137, v137, v137
	v_mul_f32_e32 v135, v135, v135
	v_fmac_f32_e32 v137, v136, v136
	v_fmac_f32_e32 v135, v134, v134
	v_add_f32_e32 v134, v137, v135
	v_add_f32_e32 v133, v134, v133
	v_mov_b32_e32 v218, v133
	v_mov_b32_e32 v134, v133
	s_nop 1
	v_permlane16_swap_b32_e32 v218, v134
	s_waitcnt lgkmcnt(0)
	v_add_f32_e32 v133, v218, v134
	v_mov_b32_e32 v218, v133
	v_mov_b32_e32 v134, v133
	s_nop 1
	v_permlane32_swap_b32_e32 v218, v134
	s_and_saveexec_b64 s[4:5], vcc
	s_cbranch_execz .LBB0_131
	s_lshl_b32 s10, s26, 11
	s_add_i32 s10, s9, s10
	v_mul_f32_e32 v136, 0x3c800000, v131
	v_lshl_add_u32 v131, v144, 5, s10
	s_waitcnt lgkmcnt(0)
	v_add_f32_e32 v137, v218, v134
	ds_write_b64 v131, v[136:137] offset:512
.LBB0_131:
	s_or_b64 exec, exec, s[4:5]
	s_waitcnt lgkmcnt(0)
	v_mov_b32_e32 v134, v85
	v_mov_b32_e32 v135, v86
	v_mov_b32_e32 v136, v84
	v_mov_b32_e32 v137, v87
	v_pk_add_f32 v[134:135], v[134:135], v[136:137]
	v_mov_b32_e32 v136, v53
	v_mov_b32_e32 v137, v54
	v_mov_b32_e32 v140, v52
	v_mov_b32_e32 v141, v55
	v_pk_add_f32 v[136:137], v[136:137], v[140:141]
	v_add_f32_e32 v131, v134, v135
	v_pk_add_f32 v[136:137], v[136:137], v[136:137] op_sel_hi:[0,1]
	v_add_f32_e32 v135, 0, v131
	v_add_f32_e32 v141, v20, v21
	v_add_f32_e32 v143, v22, v23
	v_mov_b32_e32 v140, v4
	v_mov_b32_e32 v142, v5
	v_mov_b32_e32 v136, v6
	v_mov_b32_e32 v134, v7
	v_pk_add_f32 v[140:141], v[140:141], v[142:143]
	v_pk_add_f32 v[134:135], v[136:137], v[134:135]
	s_nop 0
	v_pk_add_f32 v[134:135], v[140:141], v[134:135]
	s_nop 0
	v_add_f32_e32 v131, v134, v135
	v_mov_b32_e32 v218, v131
	v_mov_b32_e32 v133, v131
	s_nop 1
	v_permlane16_swap_b32_e32 v218, v133
	s_waitcnt lgkmcnt(0)
	v_add_f32_e32 v131, v218, v133
	v_mov_b32_e32 v218, v131
	v_mov_b32_e32 v133, v131
	s_nop 1
	v_permlane32_swap_b32_e32 v218, v133
	s_waitcnt lgkmcnt(0)
	v_add_f32_e32 v131, v218, v133
	v_fmamk_f32 v134, v131, 0xbc800000, v87
	v_fmamk_f32 v136, v131, 0xbc800000, v85
	v_fmamk_f32 v133, v131, 0xbc800000, v86
	v_fmamk_f32 v135, v131, 0xbc800000, v84
	v_mul_f32_e32 v136, v136, v136
	v_mul_f32_e32 v134, v134, v134
	v_fmac_f32_e32 v136, v135, v135
	v_fmac_f32_e32 v134, v133, v133
	v_fmamk_f32 v135, v131, 0xbc800000, v55
	v_fmamk_f32 v137, v131, 0xbc800000, v53
	v_add_f32_e32 v133, v136, v134
	v_fmamk_f32 v134, v131, 0xbc800000, v54
	v_fmamk_f32 v136, v131, 0xbc800000, v52
	v_mul_f32_e32 v137, v137, v137
	v_mul_f32_e32 v135, v135, v135
	v_fmac_f32_e32 v137, v136, v136
	v_fmac_f32_e32 v135, v134, v134
	v_add_f32_e32 v134, v137, v135
	v_fmamk_f32 v135, v131, 0xbc800000, v23
	v_fmamk_f32 v137, v131, 0xbc800000, v21
	v_add_f32_e32 v133, v133, v134
	v_fmamk_f32 v134, v131, 0xbc800000, v22
	v_fmamk_f32 v136, v131, 0xbc800000, v20
	v_mul_f32_e32 v137, v137, v137
	v_mul_f32_e32 v135, v135, v135
	v_fmac_f32_e32 v137, v136, v136
	v_fmac_f32_e32 v135, v134, v134
	v_add_f32_e32 v134, v137, v135
	v_fmamk_f32 v135, v131, 0xbc800000, v7
	v_fmamk_f32 v137, v131, 0xbc800000, v5
	v_add_f32_e32 v133, v134, v133
	v_fmamk_f32 v134, v131, 0xbc800000, v6
	v_fmamk_f32 v136, v131, 0xbc800000, v4
	v_mul_f32_e32 v137, v137, v137
	v_mul_f32_e32 v135, v135, v135
	v_fmac_f32_e32 v137, v136, v136
	v_fmac_f32_e32 v135, v134, v134
	v_add_f32_e32 v134, v137, v135
	v_add_f32_e32 v133, v134, v133
	v_mov_b32_e32 v218, v133
	v_mov_b32_e32 v134, v133
	s_nop 1
	v_permlane16_swap_b32_e32 v218, v134
	s_waitcnt lgkmcnt(0)
	v_add_f32_e32 v133, v218, v134
	v_mov_b32_e32 v218, v133
	v_mov_b32_e32 v134, v133
	s_nop 1
	v_permlane32_swap_b32_e32 v218, v134
	s_and_saveexec_b64 s[4:5], vcc
	s_cbranch_execz .LBB0_133
	s_lshl_b32 s10, s26, 11
	s_add_i32 s10, s9, s10
	v_mul_f32_e32 v136, 0x3c800000, v131
	v_lshl_add_u32 v131, v144, 5, s10
	s_waitcnt lgkmcnt(0)
	v_add_f32_e32 v137, v218, v134
	ds_write_b64 v131, v[136:137] offset:1024
.LBB0_133:
	s_or_b64 exec, exec, s[4:5]
	s_waitcnt lgkmcnt(0)
	v_mov_b32_e32 v134, v81
	v_mov_b32_e32 v135, v82
	v_mov_b32_e32 v136, v80
	v_mov_b32_e32 v137, v83
	v_pk_add_f32 v[134:135], v[134:135], v[136:137]
	v_mov_b32_e32 v136, v49
	v_mov_b32_e32 v137, v50
	v_mov_b32_e32 v140, v48
	v_mov_b32_e32 v141, v51
	v_pk_add_f32 v[136:137], v[136:137], v[140:141]
	v_add_f32_e32 v131, v134, v135
	v_pk_add_f32 v[136:137], v[136:137], v[136:137] op_sel_hi:[0,1]
	v_add_f32_e32 v135, 0, v131
	v_add_f32_e32 v141, v16, v17
	v_add_f32_e32 v143, v18, v19
	v_mov_b32_e32 v140, v0
	v_mov_b32_e32 v142, v1
	v_mov_b32_e32 v136, v2
	v_mov_b32_e32 v134, v3
	v_pk_add_f32 v[140:141], v[140:141], v[142:143]
	v_pk_add_f32 v[134:135], v[136:137], v[134:135]
	s_nop 0
	v_pk_add_f32 v[134:135], v[140:141], v[134:135]
	s_nop 0
	v_add_f32_e32 v131, v134, v135
	v_mov_b32_e32 v218, v131
	v_mov_b32_e32 v133, v131
	s_nop 1
	v_permlane16_swap_b32_e32 v218, v133
	s_waitcnt lgkmcnt(0)
	v_add_f32_e32 v131, v218, v133
	v_mov_b32_e32 v218, v131
	v_mov_b32_e32 v133, v131
	s_nop 1
	v_permlane32_swap_b32_e32 v218, v133
	s_waitcnt lgkmcnt(0)
	v_add_f32_e32 v131, v218, v133
	v_fmamk_f32 v134, v131, 0xbc800000, v83
	v_fmamk_f32 v136, v131, 0xbc800000, v81
	v_fmamk_f32 v133, v131, 0xbc800000, v82
	v_fmamk_f32 v135, v131, 0xbc800000, v80
	v_mul_f32_e32 v136, v136, v136
	v_mul_f32_e32 v134, v134, v134
	v_fmac_f32_e32 v136, v135, v135
	v_fmac_f32_e32 v134, v133, v133
	v_fmamk_f32 v135, v131, 0xbc800000, v51
	v_fmamk_f32 v137, v131, 0xbc800000, v49
	v_add_f32_e32 v133, v136, v134
	v_fmamk_f32 v134, v131, 0xbc800000, v50
	v_fmamk_f32 v136, v131, 0xbc800000, v48
	v_mul_f32_e32 v137, v137, v137
	v_mul_f32_e32 v135, v135, v135
	v_fmac_f32_e32 v137, v136, v136
	v_fmac_f32_e32 v135, v134, v134
	v_add_f32_e32 v134, v137, v135
	v_fmamk_f32 v135, v131, 0xbc800000, v19
	v_fmamk_f32 v137, v131, 0xbc800000, v17
	v_add_f32_e32 v133, v133, v134
	v_fmamk_f32 v134, v131, 0xbc800000, v18
	v_fmamk_f32 v136, v131, 0xbc800000, v16
	v_mul_f32_e32 v137, v137, v137
	v_mul_f32_e32 v135, v135, v135
	v_fmac_f32_e32 v137, v136, v136
	v_fmac_f32_e32 v135, v134, v134
	v_add_f32_e32 v134, v137, v135
	v_fmamk_f32 v135, v131, 0xbc800000, v3
	v_fmamk_f32 v137, v131, 0xbc800000, v1
	v_add_f32_e32 v133, v134, v133
	v_fmamk_f32 v134, v131, 0xbc800000, v2
	v_fmamk_f32 v136, v131, 0xbc800000, v0
	v_mul_f32_e32 v137, v137, v137
	v_mul_f32_e32 v135, v135, v135
	v_fmac_f32_e32 v137, v136, v136
	v_fmac_f32_e32 v135, v134, v134
	v_add_f32_e32 v134, v137, v135
	v_add_f32_e32 v133, v134, v133
	v_mov_b32_e32 v218, v133
	v_mov_b32_e32 v134, v133
	s_nop 1
	v_permlane16_swap_b32_e32 v218, v134
	s_waitcnt lgkmcnt(0)
	v_add_f32_e32 v133, v218, v134
	v_mov_b32_e32 v218, v133
	v_mov_b32_e32 v134, v133
	s_nop 1
	v_permlane32_swap_b32_e32 v218, v134
	s_and_saveexec_b64 s[4:5], vcc
	s_cbranch_execz .LBB0_135
	s_lshl_b32 s10, s26, 11
	s_add_i32 s10, s9, s10
	v_mul_f32_e32 v136, 0x3c800000, v131
	v_lshl_add_u32 v131, v144, 5, s10
	s_waitcnt lgkmcnt(0)
	v_add_f32_e32 v137, v218, v134
	ds_write_b64 v131, v[136:137] offset:1536
.LBB0_135:
	s_or_b64 exec, exec, s[4:5]
	s_waitcnt lgkmcnt(0)
	v_mov_b32_e32 v134, v125
	v_mov_b32_e32 v135, v126
	v_mov_b32_e32 v136, v124
	v_mov_b32_e32 v137, v127
	v_pk_add_f32 v[134:135], v[134:135], v[136:137]
	v_mov_b32_e32 v136, v109
	v_mov_b32_e32 v137, v110
	v_mov_b32_e32 v140, v108
	v_mov_b32_e32 v141, v111
	v_pk_add_f32 v[136:137], v[136:137], v[140:141]
	v_add_f32_e32 v131, v134, v135
	v_pk_add_f32 v[136:137], v[136:137], v[136:137] op_sel_hi:[0,1]
	v_add_f32_e32 v135, 0, v131
	v_add_f32_e32 v141, v76, v77
	v_add_f32_e32 v143, v78, v79
	v_mov_b32_e32 v140, v44
	v_mov_b32_e32 v142, v45
	v_mov_b32_e32 v136, v46
	v_mov_b32_e32 v134, v47
	v_pk_add_f32 v[140:141], v[140:141], v[142:143]
	v_pk_add_f32 v[134:135], v[136:137], v[134:135]
	s_nop 0
	v_pk_add_f32 v[134:135], v[140:141], v[134:135]
	s_nop 0
	v_add_f32_e32 v131, v134, v135
	v_mov_b32_e32 v218, v131
	v_mov_b32_e32 v133, v131
	s_nop 1
	v_permlane16_swap_b32_e32 v218, v133
	s_waitcnt lgkmcnt(0)
	v_add_f32_e32 v131, v218, v133
	v_mov_b32_e32 v218, v131
	v_mov_b32_e32 v133, v131
	s_nop 1
	v_permlane32_swap_b32_e32 v218, v133
	s_waitcnt lgkmcnt(0)
	v_add_f32_e32 v131, v218, v133
	v_fmamk_f32 v134, v131, 0xbc800000, v127
	v_fmamk_f32 v136, v131, 0xbc800000, v125
	v_fmamk_f32 v133, v131, 0xbc800000, v126
	v_fmamk_f32 v135, v131, 0xbc800000, v124
	v_mul_f32_e32 v136, v136, v136
	v_mul_f32_e32 v134, v134, v134
	v_fmac_f32_e32 v136, v135, v135
	v_fmac_f32_e32 v134, v133, v133
	v_fmamk_f32 v135, v131, 0xbc800000, v111
	v_fmamk_f32 v137, v131, 0xbc800000, v109
	v_add_f32_e32 v133, v136, v134
	v_fmamk_f32 v134, v131, 0xbc800000, v110
	v_fmamk_f32 v136, v131, 0xbc800000, v108
	v_mul_f32_e32 v137, v137, v137
	v_mul_f32_e32 v135, v135, v135
	v_fmac_f32_e32 v137, v136, v136
	v_fmac_f32_e32 v135, v134, v134
	v_add_f32_e32 v134, v137, v135
	v_fmamk_f32 v135, v131, 0xbc800000, v79
	v_fmamk_f32 v137, v131, 0xbc800000, v77
	v_add_f32_e32 v133, v133, v134
	v_fmamk_f32 v134, v131, 0xbc800000, v78
	v_fmamk_f32 v136, v131, 0xbc800000, v76
	v_mul_f32_e32 v137, v137, v137
	v_mul_f32_e32 v135, v135, v135
	v_fmac_f32_e32 v137, v136, v136
	v_fmac_f32_e32 v135, v134, v134
	v_add_f32_e32 v134, v137, v135
	v_fmamk_f32 v135, v131, 0xbc800000, v47
	v_fmamk_f32 v137, v131, 0xbc800000, v45
	v_add_f32_e32 v133, v134, v133
	v_fmamk_f32 v134, v131, 0xbc800000, v46
	v_fmamk_f32 v136, v131, 0xbc800000, v44
	v_mul_f32_e32 v137, v137, v137
	v_mul_f32_e32 v135, v135, v135
	v_fmac_f32_e32 v137, v136, v136
	v_fmac_f32_e32 v135, v134, v134
	v_add_f32_e32 v134, v137, v135
	v_add_f32_e32 v133, v134, v133
	v_mov_b32_e32 v218, v133
	v_mov_b32_e32 v134, v133
	s_nop 1
	v_permlane16_swap_b32_e32 v218, v134
	s_waitcnt lgkmcnt(0)
	v_add_f32_e32 v133, v218, v134
	v_mov_b32_e32 v218, v133
	v_mov_b32_e32 v134, v133
	s_nop 1
	v_permlane32_swap_b32_e32 v218, v134
	s_and_saveexec_b64 s[4:5], vcc
	s_cbranch_execz .LBB0_137
	s_lshl_b32 s10, s26, 11
	s_add_i32 s10, s9, s10
	v_mul_f32_e32 v136, 0x3c800000, v131
	v_lshl_add_u32 v131, v144, 5, s10
	s_waitcnt lgkmcnt(0)
	v_add_f32_e32 v137, v218, v134
	ds_write_b64 v131, v[136:137] offset:4096
.LBB0_137:
	s_or_b64 exec, exec, s[4:5]
	s_waitcnt lgkmcnt(0)
	v_mov_b32_e32 v134, v121
	v_mov_b32_e32 v135, v122
	v_mov_b32_e32 v136, v120
	v_mov_b32_e32 v137, v123
	v_pk_add_f32 v[134:135], v[134:135], v[136:137]
	v_mov_b32_e32 v136, v105
	v_mov_b32_e32 v137, v106
	v_mov_b32_e32 v140, v104
	v_mov_b32_e32 v141, v107
	v_pk_add_f32 v[136:137], v[136:137], v[140:141]
	v_add_f32_e32 v131, v134, v135
	v_pk_add_f32 v[136:137], v[136:137], v[136:137] op_sel_hi:[0,1]
	v_add_f32_e32 v135, 0, v131
	v_add_f32_e32 v141, v72, v73
	v_add_f32_e32 v143, v74, v75
	v_mov_b32_e32 v140, v40
	v_mov_b32_e32 v142, v41
	v_mov_b32_e32 v136, v42
	v_mov_b32_e32 v134, v43
	v_pk_add_f32 v[140:141], v[140:141], v[142:143]
	v_pk_add_f32 v[134:135], v[136:137], v[134:135]
	s_nop 0
	v_pk_add_f32 v[134:135], v[140:141], v[134:135]
	s_nop 0
	v_add_f32_e32 v131, v134, v135
	v_mov_b32_e32 v218, v131
	v_mov_b32_e32 v133, v131
	s_nop 1
	v_permlane16_swap_b32_e32 v218, v133
	s_waitcnt lgkmcnt(0)
	v_add_f32_e32 v131, v218, v133
	v_mov_b32_e32 v218, v131
	v_mov_b32_e32 v133, v131
	s_nop 1
	v_permlane32_swap_b32_e32 v218, v133
	s_waitcnt lgkmcnt(0)
	v_add_f32_e32 v131, v218, v133
	v_fmamk_f32 v134, v131, 0xbc800000, v123
	v_fmamk_f32 v136, v131, 0xbc800000, v121
	v_fmamk_f32 v133, v131, 0xbc800000, v122
	v_fmamk_f32 v135, v131, 0xbc800000, v120
	v_mul_f32_e32 v136, v136, v136
	v_mul_f32_e32 v134, v134, v134
	v_fmac_f32_e32 v136, v135, v135
	v_fmac_f32_e32 v134, v133, v133
	v_fmamk_f32 v135, v131, 0xbc800000, v107
	v_fmamk_f32 v137, v131, 0xbc800000, v105
	v_add_f32_e32 v133, v136, v134
	v_fmamk_f32 v134, v131, 0xbc800000, v106
	v_fmamk_f32 v136, v131, 0xbc800000, v104
	v_mul_f32_e32 v137, v137, v137
	v_mul_f32_e32 v135, v135, v135
	v_fmac_f32_e32 v137, v136, v136
	v_fmac_f32_e32 v135, v134, v134
	v_add_f32_e32 v134, v137, v135
	v_fmamk_f32 v135, v131, 0xbc800000, v75
	v_fmamk_f32 v137, v131, 0xbc800000, v73
	v_add_f32_e32 v133, v133, v134
	v_fmamk_f32 v134, v131, 0xbc800000, v74
	v_fmamk_f32 v136, v131, 0xbc800000, v72
	v_mul_f32_e32 v137, v137, v137
	v_mul_f32_e32 v135, v135, v135
	v_fmac_f32_e32 v137, v136, v136
	v_fmac_f32_e32 v135, v134, v134
	v_add_f32_e32 v134, v137, v135
	v_fmamk_f32 v135, v131, 0xbc800000, v43
	v_fmamk_f32 v137, v131, 0xbc800000, v41
	v_add_f32_e32 v133, v134, v133
	v_fmamk_f32 v134, v131, 0xbc800000, v42
	v_fmamk_f32 v136, v131, 0xbc800000, v40
	v_mul_f32_e32 v137, v137, v137
	v_mul_f32_e32 v135, v135, v135
	v_fmac_f32_e32 v137, v136, v136
	v_fmac_f32_e32 v135, v134, v134
	v_add_f32_e32 v134, v137, v135
	v_add_f32_e32 v133, v134, v133
	v_mov_b32_e32 v218, v133
	v_mov_b32_e32 v134, v133
	s_nop 1
	v_permlane16_swap_b32_e32 v218, v134
	s_waitcnt lgkmcnt(0)
	v_add_f32_e32 v133, v218, v134
	v_mov_b32_e32 v218, v133
	v_mov_b32_e32 v134, v133
	s_nop 1
	v_permlane32_swap_b32_e32 v218, v134
	s_and_saveexec_b64 s[4:5], vcc
	s_cbranch_execz .LBB0_139
	s_lshl_b32 s10, s26, 11
	s_add_i32 s10, s9, s10
	v_mul_f32_e32 v136, 0x3c800000, v131
	v_lshl_add_u32 v131, v144, 5, s10
	s_waitcnt lgkmcnt(0)
	v_add_f32_e32 v137, v218, v134
	ds_write_b64 v131, v[136:137] offset:4608
.LBB0_139:
	s_or_b64 exec, exec, s[4:5]
	s_waitcnt lgkmcnt(0)
	v_mov_b32_e32 v134, v117
	v_mov_b32_e32 v135, v118
	v_mov_b32_e32 v136, v116
	v_mov_b32_e32 v137, v119
	v_pk_add_f32 v[134:135], v[134:135], v[136:137]
	v_mov_b32_e32 v136, v101
	v_mov_b32_e32 v137, v102
	v_mov_b32_e32 v140, v100
	v_mov_b32_e32 v141, v103
	v_pk_add_f32 v[136:137], v[136:137], v[140:141]
	v_add_f32_e32 v131, v134, v135
	v_pk_add_f32 v[136:137], v[136:137], v[136:137] op_sel_hi:[0,1]
	v_add_f32_e32 v135, 0, v131
	v_add_f32_e32 v141, v68, v69
	v_add_f32_e32 v143, v70, v71
	v_mov_b32_e32 v140, v36
	v_mov_b32_e32 v142, v37
	v_mov_b32_e32 v136, v38
	v_mov_b32_e32 v134, v39
	v_pk_add_f32 v[140:141], v[140:141], v[142:143]
	v_pk_add_f32 v[134:135], v[136:137], v[134:135]
	s_nop 0
	v_pk_add_f32 v[134:135], v[140:141], v[134:135]
	s_nop 0
	v_add_f32_e32 v131, v134, v135
	v_mov_b32_e32 v218, v131
	v_mov_b32_e32 v133, v131
	s_nop 1
	v_permlane16_swap_b32_e32 v218, v133
	s_waitcnt lgkmcnt(0)
	v_add_f32_e32 v131, v218, v133
	v_mov_b32_e32 v218, v131
	v_mov_b32_e32 v133, v131
	s_nop 1
	v_permlane32_swap_b32_e32 v218, v133
	s_waitcnt lgkmcnt(0)
	v_add_f32_e32 v131, v218, v133
	v_fmamk_f32 v134, v131, 0xbc800000, v119
	v_fmamk_f32 v136, v131, 0xbc800000, v117
	v_fmamk_f32 v133, v131, 0xbc800000, v118
	v_fmamk_f32 v135, v131, 0xbc800000, v116
	v_mul_f32_e32 v136, v136, v136
	v_mul_f32_e32 v134, v134, v134
	v_fmac_f32_e32 v136, v135, v135
	v_fmac_f32_e32 v134, v133, v133
	v_fmamk_f32 v135, v131, 0xbc800000, v103
	v_fmamk_f32 v137, v131, 0xbc800000, v101
	v_add_f32_e32 v133, v136, v134
	v_fmamk_f32 v134, v131, 0xbc800000, v102
	v_fmamk_f32 v136, v131, 0xbc800000, v100
	v_mul_f32_e32 v137, v137, v137
	v_mul_f32_e32 v135, v135, v135
	v_fmac_f32_e32 v137, v136, v136
	v_fmac_f32_e32 v135, v134, v134
	v_add_f32_e32 v134, v137, v135
	v_fmamk_f32 v135, v131, 0xbc800000, v71
	v_fmamk_f32 v137, v131, 0xbc800000, v69
	v_add_f32_e32 v133, v133, v134
	v_fmamk_f32 v134, v131, 0xbc800000, v70
	v_fmamk_f32 v136, v131, 0xbc800000, v68
	v_mul_f32_e32 v137, v137, v137
	v_mul_f32_e32 v135, v135, v135
	v_fmac_f32_e32 v137, v136, v136
	v_fmac_f32_e32 v135, v134, v134
	v_add_f32_e32 v134, v137, v135
	v_fmamk_f32 v135, v131, 0xbc800000, v39
	v_fmamk_f32 v137, v131, 0xbc800000, v37
	v_add_f32_e32 v133, v134, v133
	v_fmamk_f32 v134, v131, 0xbc800000, v38
	v_fmamk_f32 v136, v131, 0xbc800000, v36
	v_mul_f32_e32 v137, v137, v137
	v_mul_f32_e32 v135, v135, v135
	v_fmac_f32_e32 v137, v136, v136
	v_fmac_f32_e32 v135, v134, v134
	v_add_f32_e32 v134, v137, v135
	v_add_f32_e32 v133, v134, v133
	v_mov_b32_e32 v218, v133
	v_mov_b32_e32 v134, v133
	s_nop 1
	v_permlane16_swap_b32_e32 v218, v134
	s_waitcnt lgkmcnt(0)
	v_add_f32_e32 v133, v218, v134
	v_mov_b32_e32 v218, v133
	v_mov_b32_e32 v134, v133
	s_nop 1
	v_permlane32_swap_b32_e32 v218, v134
	s_and_saveexec_b64 s[4:5], vcc
	s_cbranch_execz .LBB0_141
	s_lshl_b32 s10, s26, 11
	s_add_i32 s10, s9, s10
	v_mul_f32_e32 v136, 0x3c800000, v131
	v_lshl_add_u32 v131, v144, 5, s10
	s_waitcnt lgkmcnt(0)
	v_add_f32_e32 v137, v218, v134
	ds_write_b64 v131, v[136:137] offset:5120
.LBB0_141:
	s_or_b64 exec, exec, s[4:5]
	s_waitcnt lgkmcnt(0)
	v_mov_b32_e32 v134, v113
	v_mov_b32_e32 v135, v114
	v_mov_b32_e32 v136, v112
	v_mov_b32_e32 v137, v115
	v_pk_add_f32 v[134:135], v[134:135], v[136:137]
	v_mov_b32_e32 v136, v97
	v_mov_b32_e32 v137, v98
	v_mov_b32_e32 v140, v96
	v_mov_b32_e32 v141, v99
	v_pk_add_f32 v[136:137], v[136:137], v[140:141]
	v_add_f32_e32 v131, v134, v135
	v_pk_add_f32 v[136:137], v[136:137], v[136:137] op_sel_hi:[0,1]
	v_add_f32_e32 v135, 0, v131
	v_add_f32_e32 v141, v64, v65
	v_add_f32_e32 v143, v66, v67
	v_mov_b32_e32 v140, v32
	v_mov_b32_e32 v142, v33
	v_mov_b32_e32 v136, v34
	v_mov_b32_e32 v134, v35
	v_pk_add_f32 v[140:141], v[140:141], v[142:143]
	v_pk_add_f32 v[134:135], v[136:137], v[134:135]
	s_nop 0
	v_pk_add_f32 v[134:135], v[140:141], v[134:135]
	s_nop 0
	v_add_f32_e32 v131, v134, v135
	v_mov_b32_e32 v218, v131
	v_mov_b32_e32 v133, v131
	s_nop 1
	v_permlane16_swap_b32_e32 v218, v133
	s_waitcnt lgkmcnt(0)
	v_add_f32_e32 v131, v218, v133
	v_mov_b32_e32 v218, v131
	v_mov_b32_e32 v133, v131
	s_nop 1
	v_permlane32_swap_b32_e32 v218, v133
	s_waitcnt lgkmcnt(0)
	v_add_f32_e32 v131, v218, v133
	v_fmamk_f32 v134, v131, 0xbc800000, v115
	v_fmamk_f32 v136, v131, 0xbc800000, v113
	v_fmamk_f32 v133, v131, 0xbc800000, v114
	v_fmamk_f32 v135, v131, 0xbc800000, v112
	v_mul_f32_e32 v136, v136, v136
	v_mul_f32_e32 v134, v134, v134
	v_fmac_f32_e32 v136, v135, v135
	v_fmac_f32_e32 v134, v133, v133
	v_fmamk_f32 v135, v131, 0xbc800000, v99
	v_fmamk_f32 v137, v131, 0xbc800000, v97
	v_add_f32_e32 v133, v136, v134
	v_fmamk_f32 v134, v131, 0xbc800000, v98
	v_fmamk_f32 v136, v131, 0xbc800000, v96
	v_mul_f32_e32 v137, v137, v137
	v_mul_f32_e32 v135, v135, v135
	v_fmac_f32_e32 v137, v136, v136
	v_fmac_f32_e32 v135, v134, v134
	v_add_f32_e32 v134, v137, v135
	v_fmamk_f32 v135, v131, 0xbc800000, v67
	v_fmamk_f32 v137, v131, 0xbc800000, v65
	v_add_f32_e32 v133, v133, v134
	v_fmamk_f32 v134, v131, 0xbc800000, v66
	v_fmamk_f32 v136, v131, 0xbc800000, v64
	v_mul_f32_e32 v137, v137, v137
	v_mul_f32_e32 v135, v135, v135
	v_fmac_f32_e32 v137, v136, v136
	v_fmac_f32_e32 v135, v134, v134
	v_add_f32_e32 v134, v137, v135
	v_fmamk_f32 v135, v131, 0xbc800000, v35
	v_fmamk_f32 v137, v131, 0xbc800000, v33
	v_add_f32_e32 v133, v134, v133
	v_fmamk_f32 v134, v131, 0xbc800000, v34
	v_fmamk_f32 v136, v131, 0xbc800000, v32
	v_mul_f32_e32 v137, v137, v137
	v_mul_f32_e32 v135, v135, v135
	v_fmac_f32_e32 v137, v136, v136
	v_fmac_f32_e32 v135, v134, v134
	v_add_f32_e32 v134, v137, v135
	v_add_f32_e32 v133, v134, v133
	v_mov_b32_e32 v218, v133
	v_mov_b32_e32 v130, v133
	s_nop 1
	v_permlane16_swap_b32_e32 v218, v130
	s_waitcnt lgkmcnt(0)
	v_add_f32_e32 v130, v218, v130
	v_mov_b32_e32 v218, v130
	v_mov_b32_e32 v128, v130
	s_nop 1
	v_permlane32_swap_b32_e32 v218, v128
	s_and_saveexec_b64 s[4:5], vcc
	s_cbranch_execz .LBB0_143
	s_lshl_b32 s10, s26, 11
	s_add_i32 s9, s9, s10
	v_mul_f32_e32 v134, 0x3c800000, v131
	v_lshl_add_u32 v131, v144, 5, s9
	s_waitcnt lgkmcnt(0)
	v_add_f32_e32 v135, v218, v128
	ds_write_b64 v131, v[134:135] offset:5632
